# cross attention K/V chunks staged by LDS-DMA (global_load_lds_dwordx4 with the slot rotation applied on the source addresses) instead of VGPR + ds_write
# baseline (speedup 1.0000x reference)
; #define LAS __attribute__((address_space(3)))
; __device__ __forceinline__ int opaque_tid() { int t = (int)threadIdx.x; asm volatile("" : "+v"(t)); return t; }
; #define XLOAD(kvbase, c8) do { const bf16_t* _src = (kvbase) + (((c8) >= 4) ? 2048 : 0) + ((c8) & 3) * 128 + piece * 8; \
;         _Pragma("unroll") for (int _it = 0; _it < 8; ++_it) pre[_it] = *(const u32x4*)(_src + (size_t)(srow + 32 * _it) * 4096); } while (0)
; #define XSTORE(buf) do { _Pragma("unroll") for (int _it = 0; _it < 8; ++_it) *(LAS u32x4*)((buf) + (srow + 32 * _it) * KV_STRIDE + piece * 16) = pre[_it]; } while (0)
; __device__ void cross_items(const Params& p, LAS unsigned char* lds) {
;     const int tid = opaque_tid(), lane = tid & 63, w = __builtin_amdgcn_readfirstlane(tid >> 6), idx = lane & 15, g = lane >> 4;
;     unsigned char* ws = p.ws;
;     bf16_t* oc = (bf16_t*)(ws + OFF_OC);
;     const unsigned lbase = (unsigned)(size_t)lds;
;     const int piece = tid & 15, srow = tid >> 4;
;     const int G = (int)gridDim.x;
;     u32x4 pre[8];
;     ...
;     const int pmx = 8 * ((int)blockIdx.x & 7) + ((int)blockIdx.x >> 5), hdx = ((int)blockIdx.x >> 3) & 3;
;     const int item0 = (pmx >> 4) * 128 + hdx * 32 + 2 * (pmx & 15);
;     { const bf16_t* kvb0 = (const bf16_t*)(ws + OFF_MKV) + (size_t)((item0 >> 7) * 256) * 4096 + ((item0 >> 5) & 3) * 512; XLOAD(kvb0, 0); }
;     for (int item = item0; item < item0 + 2; ++item) {
;         const int b = item >> 7, head = (item >> 5) & 3, qb = item & 31;
;         const size_t tok = (size_t)(b * SEQ + qb * 128 + 16 * w + idx);
;         const bf16_t* qrow = (const bf16_t*)(ws + OFF_B1) + tok * DM + head * 512 + 8 * g;
;         const bf16_t* kvb = (const bf16_t*)(ws + OFF_MKV) + (size_t)(b * 256) * 4096 + head * 512;
;         f32x4 sc[16];
; #pragma unroll
;         for (int kt = 0; kt < 16; ++kt) sc[kt] = (f32x4){0.f, 0.f, 0.f, 0.f};
;         for (int c = 0; c < 4; ++c) {
;             LAS unsigned char* buf = lds + (c & 1) * KV_BUF;
;             XSTORE(buf);
;             bf16x8 qf[4];
; #pragma unroll
;             for (int ks = 0; ks < 4; ++ks) qf[ks] = *(const bf16x8*)(qrow + c * 128 + 32 * ks);
;             XLOAD(kvb, c + 1);
.LBB0_391:
	s_or_b64 exec, exec, s[0:1]
	v_mov_b32_e32 v40, v212
	s_waitcnt vmcnt(0) lgkmcnt(0)
	s_barrier
	v_readlane_b32 s0, v254, 29
	v_and_b32_e32 v243, 63, v212
	v_lshrrev_b32_e32 v242, 6, v212
	s_nop 1
	v_readfirstlane_b32 s4, v242
	s_lshr_b32 s0, s0, 9
	s_and_b32 s1, s0, 7
	s_lshl_b32 s1, s1, 3
	s_lshr_b32 s2, s0, 5
	s_add_i32 s1, s1, s2
	s_lshr_b32 s2, s0, 3
	s_and_b32 s2, s2, 3
	s_lshr_b32 s3, s1, 4
	s_add_u32 s6, s92, 0x1000
	s_addc_u32 s7, s93, 0
	v_and_b32_e32 v4, 15, v243
	v_lshrrev_b32_e32 v5, 4, v243
	v_and_b32_e32 v6, 15, v212
	v_lshrrev_b32_e32 v7, 4, v212
	v_and_b32_e32 v8, 7, v7
	v_lshl_add_u32 v8, v8, 1, v6
	v_and_b32_e32 v8, 15, v8
	v_lshlrev_b32_e32 v8, 4, v8
	v_lshl_add_u32 v0, v7, 8, v8
	v_add_u32_e32 v1, 0x10000, v0
	v_and_b32_e32 v9, 7, v4
	v_lshlrev_b32_e32 v9, 1, v9
	v_add_u32_e32 v9, v9, v5
	v_add_u32_e32 v10, 0, v9
	v_and_b32_e32 v10, 15, v10
	v_lshlrev_b32_e32 v10, 4, v10
	v_lshl_add_u32 v2, v4, 8, v10
	v_add_u32_e32 v10, 4, v9
	v_and_b32_e32 v10, 15, v10
	v_lshlrev_b32_e32 v10, 4, v10
	v_lshl_add_u32 v208, v4, 8, v10
	v_add_u32_e32 v10, 8, v9
	v_and_b32_e32 v10, 15, v10
	v_lshlrev_b32_e32 v10, 4, v10
	v_lshl_add_u32 v209, v4, 8, v10
	v_add_u32_e32 v10, 12, v9
	v_and_b32_e32 v10, 15, v10
	v_lshlrev_b32_e32 v10, 4, v10
	v_lshl_add_u32 v210, v4, 8, v10
	s_lshl_b32 s5, s1, 20
	s_lshl_b32 s8, s4, 16
	s_add_i32 s5, s5, s8
	s_lshl_b32 s8, s2, 10
	s_add_i32 s5, s5, s8
	v_lshlrev_b32_e32 v246, 12, v4
	v_add_u32_e32 v246, s5, v246
	v_lshl_add_u32 v248, v5, 3, v246
	v_add_u32_e32 v248, 0xd100000, v248
	v_add_u32_e32 v249, 0x80000, v248
	v_lshl_add_u32 v246, v5, 4, v246
	v_add_u32_e32 v247, 0x80000, v246
	s_lshl_b32 s5, s3, 21
	s_add_i32 s5, s5, s8
	s_add_i32 s5, s5, 0xc400000
	s_lshl_b32 s8, s4, 18
	s_add_i32 s5, s5, s8
	v_lshlrev_b32_e32 v8, 1, v5
	v_sub_u32_e32 v8, v4, v8
	v_and_b32_e32 v8, 15, v8
	v_lshlrev_b32_e32 v8, 4, v8
	v_lshl_add_u32 v164, v5, 13, v8
	v_add_u32_e32 v164, s5, v164
	v_xor_b32_e32 v165, 0x80, v164
	s_lshl_b32 s10, s4, 13
	s_mov_b32 s9, 0
	s_and_b32 s2, s9, 3
	s_lshl_b32 s2, s2, 8
	s_lshr_b32 s3, s9, 2
	s_lshl_b32 s3, s3, 12
	s_add_i32 s2, s2, s3
	s_add_u32 s0, s92, s2
	s_addc_u32 s1, s93, 0
	s_add_i32 s9, s9, 1
	s_mov_b32 m0, s10
	s_nop 0
	global_load_lds_dwordx4 v164, s[0:1]
	s_add_u32 s0, s0, 0x8000
	s_addc_u32 s1, s1, 0
	s_add_i32 m0, s10, 0x400
	s_nop 0
	global_load_lds_dwordx4 v165, s[0:1]
	s_add_u32 s0, s0, 0x8000
	s_addc_u32 s1, s1, 0
	s_add_i32 m0, s10, 0x800
	s_nop 0
	global_load_lds_dwordx4 v164, s[0:1]
	s_add_u32 s0, s0, 0x8000
	s_addc_u32 s1, s1, 0
	s_add_i32 m0, s10, 0xc00
	s_nop 0
	global_load_lds_dwordx4 v165, s[0:1]
	s_add_u32 s0, s0, 0x8000
	s_addc_u32 s1, s1, 0
	s_add_i32 m0, s10, 0x1000
	s_nop 0
	global_load_lds_dwordx4 v164, s[0:1]
	s_add_u32 s0, s0, 0x8000
	s_addc_u32 s1, s1, 0
	s_add_i32 m0, s10, 0x1400
	s_nop 0
	global_load_lds_dwordx4 v165, s[0:1]
	s_add_u32 s0, s0, 0x8000
	s_addc_u32 s1, s1, 0
	s_add_i32 m0, s10, 0x1800
	s_nop 0
	global_load_lds_dwordx4 v164, s[0:1]
	s_add_u32 s0, s0, 0x8000
	s_addc_u32 s1, s1, 0
	s_add_i32 m0, s10, 0x1c00
	s_nop 0
	global_load_lds_dwordx4 v165, s[0:1]
	s_xor_b32 s10, s10, 0x10000
	global_load_dwordx4 v[132:135], v246, s[92:93] offset:0
	global_load_dwordx4 v[136:139], v246, s[92:93] offset:64
	global_load_dwordx4 v[148:151], v247, s[92:93] offset:0
	global_load_dwordx4 v[152:155], v247, s[92:93] offset:64
	global_load_dwordx4 v[140:143], v246, s[92:93] offset:128
	global_load_dwordx4 v[144:147], v246, s[92:93] offset:192
	global_load_dwordx4 v[156:159], v247, s[92:93] offset:128
	global_load_dwordx4 v[160:163], v247, s[92:93] offset:192
	v_mov_b32_e32 v4, 0
	v_mov_b32_e32 v5, 0
	v_mov_b32_e32 v6, 0
	v_mov_b32_e32 v7, 0
	v_mov_b32_e32 v8, 0
	v_mov_b32_e32 v9, 0
	v_mov_b32_e32 v10, 0
	v_mov_b32_e32 v11, 0
	v_mov_b32_e32 v12, 0
	v_mov_b32_e32 v13, 0
	v_mov_b32_e32 v14, 0
	v_mov_b32_e32 v15, 0
	v_mov_b32_e32 v16, 0
	v_mov_b32_e32 v17, 0
	v_mov_b32_e32 v18, 0
	v_mov_b32_e32 v19, 0
	v_mov_b32_e32 v20, 0
	v_mov_b32_e32 v21, 0
	v_mov_b32_e32 v22, 0
	v_mov_b32_e32 v23, 0
	v_mov_b32_e32 v24, 0
	v_mov_b32_e32 v25, 0
	v_mov_b32_e32 v26, 0
	v_mov_b32_e32 v27, 0
	v_mov_b32_e32 v28, 0
	v_mov_b32_e32 v29, 0
	v_mov_b32_e32 v30, 0
	v_mov_b32_e32 v31, 0
	v_mov_b32_e32 v32, 0
	v_mov_b32_e32 v33, 0
	v_mov_b32_e32 v34, 0
	v_mov_b32_e32 v35, 0
	v_mov_b32_e32 v36, 0
	v_mov_b32_e32 v37, 0
	v_mov_b32_e32 v38, 0
	v_mov_b32_e32 v39, 0
	v_mov_b32_e32 v40, 0
	v_mov_b32_e32 v41, 0
	v_mov_b32_e32 v42, 0
	v_mov_b32_e32 v43, 0
	v_mov_b32_e32 v44, 0
	v_mov_b32_e32 v45, 0
	v_mov_b32_e32 v46, 0
	v_mov_b32_e32 v47, 0
	v_mov_b32_e32 v48, 0
	v_mov_b32_e32 v49, 0
	v_mov_b32_e32 v50, 0
	v_mov_b32_e32 v51, 0
	v_mov_b32_e32 v52, 0
	v_mov_b32_e32 v53, 0
	v_mov_b32_e32 v54, 0
	v_mov_b32_e32 v55, 0
	v_mov_b32_e32 v56, 0
	v_mov_b32_e32 v57, 0
	v_mov_b32_e32 v58, 0
	v_mov_b32_e32 v59, 0
	v_mov_b32_e32 v60, 0
	v_mov_b32_e32 v61, 0
	v_mov_b32_e32 v62, 0
	v_mov_b32_e32 v63, 0
	v_mov_b32_e32 v64, 0
	v_mov_b32_e32 v65, 0
	v_mov_b32_e32 v66, 0
	v_mov_b32_e32 v67, 0
	v_mov_b32_e32 v68, 0
	v_mov_b32_e32 v69, 0
	v_mov_b32_e32 v70, 0
	v_mov_b32_e32 v71, 0
	v_mov_b32_e32 v72, 0
	v_mov_b32_e32 v73, 0
	v_mov_b32_e32 v74, 0
	v_mov_b32_e32 v75, 0
	v_mov_b32_e32 v76, 0
	v_mov_b32_e32 v77, 0
	v_mov_b32_e32 v78, 0
	v_mov_b32_e32 v79, 0
	v_mov_b32_e32 v80, 0
	v_mov_b32_e32 v81, 0
	v_mov_b32_e32 v82, 0
	v_mov_b32_e32 v83, 0
	v_mov_b32_e32 v84, 0
	v_mov_b32_e32 v85, 0
	v_mov_b32_e32 v86, 0
	v_mov_b32_e32 v87, 0
	v_mov_b32_e32 v88, 0
	v_mov_b32_e32 v89, 0
	v_mov_b32_e32 v90, 0
	v_mov_b32_e32 v91, 0
	v_mov_b32_e32 v92, 0
	v_mov_b32_e32 v93, 0
	v_mov_b32_e32 v94, 0
	v_mov_b32_e32 v95, 0
	v_mov_b32_e32 v96, 0
	v_mov_b32_e32 v97, 0
	v_mov_b32_e32 v98, 0
	v_mov_b32_e32 v99, 0
	v_mov_b32_e32 v100, 0
	v_mov_b32_e32 v101, 0
	v_mov_b32_e32 v102, 0
	v_mov_b32_e32 v103, 0
	v_mov_b32_e32 v104, 0
	v_mov_b32_e32 v105, 0
	v_mov_b32_e32 v106, 0
	v_mov_b32_e32 v107, 0
	v_mov_b32_e32 v108, 0
	v_mov_b32_e32 v109, 0
	v_mov_b32_e32 v110, 0
	v_mov_b32_e32 v111, 0
	v_mov_b32_e32 v112, 0
	v_mov_b32_e32 v113, 0
	v_mov_b32_e32 v114, 0
	v_mov_b32_e32 v115, 0
	v_mov_b32_e32 v116, 0
	v_mov_b32_e32 v117, 0
	v_mov_b32_e32 v118, 0
	v_mov_b32_e32 v119, 0
	v_mov_b32_e32 v120, 0
	v_mov_b32_e32 v121, 0
	v_mov_b32_e32 v122, 0
	v_mov_b32_e32 v123, 0
	v_mov_b32_e32 v124, 0
	v_mov_b32_e32 v125, 0
	v_mov_b32_e32 v126, 0
	v_mov_b32_e32 v127, 0
	v_mov_b32_e32 v128, 0
	v_mov_b32_e32 v129, 0
	v_mov_b32_e32 v130, 0
	v_mov_b32_e32 v131, 0
	s_mov_b32 s4, 0
; #define LAS __attribute__((address_space(3)))
; __device__ __forceinline__ f32x4 mfma16(bf16x8 a, bf16x8 b, f32x4 c) { return __builtin_amdgcn_mfma_f32_16x16x32_bf16(a, b, c, 0, 0, 0); }
; #define LDS_BARRIER() do { asm volatile("s_waitcnt lgkmcnt(0)" ::: "memory"); __builtin_amdgcn_s_barrier(); asm volatile("" ::: "memory"); } while (0)
; #define XLOAD(kvbase, c8) do { const bf16_t* _src = (kvbase) + (((c8) >= 4) ? 2048 : 0) + ((c8) & 3) * 128 + piece * 8; \
;         _Pragma("unroll") for (int _it = 0; _it < 8; ++_it) pre[_it] = *(const u32x4*)(_src + (size_t)(srow + 32 * _it) * 4096); } while (0)
; #define XSTORE(buf) do { _Pragma("unroll") for (int _it = 0; _it < 8; ++_it) *(LAS u32x4*)((buf) + (srow + 32 * _it) * KV_STRIDE + piece * 16) = pre[_it]; } while (0)
; __device__ void cross_items(const Params& p, LAS unsigned char* lds) {
;     ...
;         for (int c = 0; c < 4; ++c) {
;             LAS unsigned char* buf = lds + (c & 1) * KV_BUF;
;             XSTORE(buf);
;             bf16x8 qf[4];
; #pragma unroll
;             for (int ks = 0; ks < 4; ++ks) qf[ks] = *(const bf16x8*)(qrow + c * 128 + 32 * ks);
;             XLOAD(kvb, c + 1);
;             LDS_BARRIER();
; #pragma unroll
;             for (int kt = 0; kt < 16; ++kt)
; #pragma unroll
;                 for (int ks = 0; ks < 4; ++ks) sc[kt] = mfma16(frag_row(buf, KV_STRIDE, 16 * kt, 32 * ks, idx, g), qf[ks], sc[kt]);
;         }
.Lxa_qk:
	s_waitcnt vmcnt(8)
	s_barrier
	s_and_b32 s2, s9, 3
	s_lshl_b32 s2, s2, 8
	s_lshr_b32 s3, s9, 2
	s_lshl_b32 s3, s3, 12
	s_add_i32 s2, s2, s3
	s_add_u32 s0, s92, s2
	s_addc_u32 s1, s93, 0
	s_add_i32 s9, s9, 1
	s_mov_b32 m0, s10
	s_nop 0
	global_load_lds_dwordx4 v164, s[0:1]
	s_add_u32 s0, s0, 0x8000
	s_addc_u32 s1, s1, 0
	s_add_i32 m0, s10, 0x400
	s_nop 0
	global_load_lds_dwordx4 v165, s[0:1]
	s_add_u32 s0, s0, 0x8000
	s_addc_u32 s1, s1, 0
	s_add_i32 m0, s10, 0x800
	s_nop 0
	global_load_lds_dwordx4 v164, s[0:1]
	s_add_u32 s0, s0, 0x8000
	s_addc_u32 s1, s1, 0
	s_add_i32 m0, s10, 0xc00
	s_nop 0
	global_load_lds_dwordx4 v165, s[0:1]
	s_add_u32 s0, s0, 0x8000
	s_addc_u32 s1, s1, 0
	s_add_i32 m0, s10, 0x1000
	s_nop 0
	global_load_lds_dwordx4 v164, s[0:1]
	s_add_u32 s0, s0, 0x8000
	s_addc_u32 s1, s1, 0
	s_add_i32 m0, s10, 0x1400
	s_nop 0
	global_load_lds_dwordx4 v165, s[0:1]
	s_add_u32 s0, s0, 0x8000
	s_addc_u32 s1, s1, 0
	s_add_i32 m0, s10, 0x1800
	s_nop 0
	global_load_lds_dwordx4 v164, s[0:1]
	s_add_u32 s0, s0, 0x8000
	s_addc_u32 s1, s1, 0
	s_add_i32 m0, s10, 0x1c00
	s_nop 0
	global_load_lds_dwordx4 v165, s[0:1]
	s_xor_b32 s10, s10, 0x10000
	ds_read_b128 v[196:199], v2
	ds_read_b128 v[200:203], v2 offset:4096
	ds_read_b128 v[204:207], v208
	ds_read_b128 v[220:223], v208 offset:4096
	ds_read_b128 v[230:233], v2 offset:8192
	ds_read_b128 v[234:237], v2 offset:12288
	ds_read_b128 v[238:241], v208 offset:8192
	s_waitcnt vmcnt(12) lgkmcnt(6)
	v_mfma_f32_16x16x32_bf16 v[4:7], v[196:199], v[132:135], v[4:7]
	v_mfma_f32_16x16x32_bf16 v[68:71], v[196:199], v[148:151], v[68:71]
	ds_read_b128 v[196:199], v208 offset:12288
	s_waitcnt lgkmcnt(6)
	v_mfma_f32_16x16x32_bf16 v[8:11], v[200:203], v[132:135], v[8:11]
	v_mfma_f32_16x16x32_bf16 v[72:75], v[200:203], v[148:151], v[72:75]
	ds_read_b128 v[200:203], v2 offset:16384
	s_waitcnt lgkmcnt(6)
	v_mfma_f32_16x16x32_bf16 v[4:7], v[204:207], v[136:139], v[4:7]
	v_mfma_f32_16x16x32_bf16 v[68:71], v[204:207], v[152:155], v[68:71]
	ds_read_b128 v[204:207], v2 offset:20480
	s_waitcnt lgkmcnt(6)
	v_mfma_f32_16x16x32_bf16 v[8:11], v[220:223], v[136:139], v[8:11]
	v_mfma_f32_16x16x32_bf16 v[72:75], v[220:223], v[152:155], v[72:75]
	ds_read_b128 v[220:223], v208 offset:16384
	s_waitcnt lgkmcnt(6)
	v_mfma_f32_16x16x32_bf16 v[12:15], v[230:233], v[132:135], v[12:15]
	v_mfma_f32_16x16x32_bf16 v[76:79], v[230:233], v[148:151], v[76:79]
	ds_read_b128 v[230:233], v208 offset:20480
	s_waitcnt lgkmcnt(6)
	v_mfma_f32_16x16x32_bf16 v[16:19], v[234:237], v[132:135], v[16:19]
	v_mfma_f32_16x16x32_bf16 v[80:83], v[234:237], v[148:151], v[80:83]
	ds_read_b128 v[234:237], v2 offset:24576
	s_waitcnt lgkmcnt(6)
	v_mfma_f32_16x16x32_bf16 v[12:15], v[238:241], v[136:139], v[12:15]
	v_mfma_f32_16x16x32_bf16 v[76:79], v[238:241], v[152:155], v[76:79]
	ds_read_b128 v[238:241], v2 offset:28672
	s_waitcnt lgkmcnt(6)
	v_mfma_f32_16x16x32_bf16 v[16:19], v[196:199], v[136:139], v[16:19]
	v_mfma_f32_16x16x32_bf16 v[80:83], v[196:199], v[152:155], v[80:83]
	ds_read_b128 v[196:199], v208 offset:24576
	s_waitcnt lgkmcnt(6)
	v_mfma_f32_16x16x32_bf16 v[20:23], v[200:203], v[132:135], v[20:23]
	v_mfma_f32_16x16x32_bf16 v[84:87], v[200:203], v[148:151], v[84:87]
	ds_read_b128 v[200:203], v208 offset:28672
	s_waitcnt lgkmcnt(6)
	v_mfma_f32_16x16x32_bf16 v[24:27], v[204:207], v[132:135], v[24:27]
	v_mfma_f32_16x16x32_bf16 v[88:91], v[204:207], v[148:151], v[88:91]
	ds_read_b128 v[204:207], v2 offset:32768
	s_waitcnt lgkmcnt(6)
	v_mfma_f32_16x16x32_bf16 v[20:23], v[220:223], v[136:139], v[20:23]
	v_mfma_f32_16x16x32_bf16 v[84:87], v[220:223], v[152:155], v[84:87]
	ds_read_b128 v[220:223], v2 offset:36864
	s_waitcnt lgkmcnt(6)
	v_mfma_f32_16x16x32_bf16 v[24:27], v[230:233], v[136:139], v[24:27]
	v_mfma_f32_16x16x32_bf16 v[88:91], v[230:233], v[152:155], v[88:91]
	ds_read_b128 v[230:233], v208 offset:32768
	s_waitcnt lgkmcnt(6)
	v_mfma_f32_16x16x32_bf16 v[28:31], v[234:237], v[132:135], v[28:31]
	v_mfma_f32_16x16x32_bf16 v[92:95], v[234:237], v[148:151], v[92:95]
	ds_read_b128 v[234:237], v208 offset:36864
	s_waitcnt lgkmcnt(6)
	v_mfma_f32_16x16x32_bf16 v[32:35], v[238:241], v[132:135], v[32:35]
	v_mfma_f32_16x16x32_bf16 v[96:99], v[238:241], v[148:151], v[96:99]
	ds_read_b128 v[238:241], v2 offset:40960
	s_waitcnt lgkmcnt(6)
	v_mfma_f32_16x16x32_bf16 v[28:31], v[196:199], v[136:139], v[28:31]
	v_mfma_f32_16x16x32_bf16 v[92:95], v[196:199], v[152:155], v[92:95]
	ds_read_b128 v[196:199], v2 offset:45056
	s_waitcnt lgkmcnt(6)
	v_mfma_f32_16x16x32_bf16 v[32:35], v[200:203], v[136:139], v[32:35]
	v_mfma_f32_16x16x32_bf16 v[96:99], v[200:203], v[152:155], v[96:99]
	ds_read_b128 v[200:203], v208 offset:40960
	s_waitcnt lgkmcnt(6)
	v_mfma_f32_16x16x32_bf16 v[36:39], v[204:207], v[132:135], v[36:39]
	v_mfma_f32_16x16x32_bf16 v[100:103], v[204:207], v[148:151], v[100:103]
	ds_read_b128 v[204:207], v208 offset:45056
	s_waitcnt lgkmcnt(6)
	v_mfma_f32_16x16x32_bf16 v[40:43], v[220:223], v[132:135], v[40:43]
	v_mfma_f32_16x16x32_bf16 v[104:107], v[220:223], v[148:151], v[104:107]
	ds_read_b128 v[220:223], v2 offset:49152
	s_waitcnt lgkmcnt(6)
	v_mfma_f32_16x16x32_bf16 v[36:39], v[230:233], v[136:139], v[36:39]
	v_mfma_f32_16x16x32_bf16 v[100:103], v[230:233], v[152:155], v[100:103]
	ds_read_b128 v[230:233], v2 offset:53248
	s_waitcnt lgkmcnt(6)
	v_mfma_f32_16x16x32_bf16 v[40:43], v[234:237], v[136:139], v[40:43]
	v_mfma_f32_16x16x32_bf16 v[104:107], v[234:237], v[152:155], v[104:107]
	ds_read_b128 v[234:237], v208 offset:49152
	s_waitcnt lgkmcnt(6)
	v_mfma_f32_16x16x32_bf16 v[44:47], v[238:241], v[132:135], v[44:47]
	v_mfma_f32_16x16x32_bf16 v[108:111], v[238:241], v[148:151], v[108:111]
	ds_read_b128 v[238:241], v208 offset:53248
	s_waitcnt lgkmcnt(6)
; __device__ __forceinline__ f32x4 mfma16(bf16x8 a, bf16x8 b, f32x4 c) { return __builtin_amdgcn_mfma_f32_16x16x32_bf16(a, b, c, 0, 0, 0); }
; #define LDS_BARRIER() do { asm volatile("s_waitcnt lgkmcnt(0)" ::: "memory"); __builtin_amdgcn_s_barrier(); asm volatile("" ::: "memory"); } while (0)
; #define XLOAD(kvbase, c8) do { const bf16_t* _src = (kvbase) + (((c8) >= 4) ? 2048 : 0) + ((c8) & 3) * 128 + piece * 8; \
;         _Pragma("unroll") for (int _it = 0; _it < 8; ++_it) pre[_it] = *(const u32x4*)(_src + (size_t)(srow + 32 * _it) * 4096); } while (0)
; __device__ void cross_items(const Params& p, LAS unsigned char* lds) {
;     ...
;             for (int ks = 0; ks < 4; ++ks) qf[ks] = *(const bf16x8*)(qrow + c * 128 + 32 * ks);
;             XLOAD(kvb, c + 1);
;             LDS_BARRIER();
; #pragma unroll
;             for (int kt = 0; kt < 16; ++kt)
; #pragma unroll
;                 for (int ks = 0; ks < 4; ++ks) sc[kt] = mfma16(frag_row(buf, KV_STRIDE, 16 * kt, 32 * ks, idx, g), qf[ks], sc[kt]);
	v_mfma_f32_16x16x32_bf16 v[48:51], v[196:199], v[132:135], v[48:51]
	v_mfma_f32_16x16x32_bf16 v[112:115], v[196:199], v[148:151], v[112:115]
	ds_read_b128 v[196:199], v2 offset:57344
	s_waitcnt lgkmcnt(6)
	v_mfma_f32_16x16x32_bf16 v[44:47], v[200:203], v[136:139], v[44:47]
	v_mfma_f32_16x16x32_bf16 v[108:111], v[200:203], v[152:155], v[108:111]
	ds_read_b128 v[200:203], v2 offset:61440
	s_waitcnt lgkmcnt(6)
	v_mfma_f32_16x16x32_bf16 v[48:51], v[204:207], v[136:139], v[48:51]
	v_mfma_f32_16x16x32_bf16 v[112:115], v[204:207], v[152:155], v[112:115]
	ds_read_b128 v[204:207], v208 offset:57344
	s_waitcnt lgkmcnt(6)
	v_mfma_f32_16x16x32_bf16 v[52:55], v[220:223], v[132:135], v[52:55]
	v_mfma_f32_16x16x32_bf16 v[116:119], v[220:223], v[148:151], v[116:119]
	ds_read_b128 v[220:223], v208 offset:61440
	s_waitcnt lgkmcnt(6)
	v_mfma_f32_16x16x32_bf16 v[56:59], v[230:233], v[132:135], v[56:59]
	v_mfma_f32_16x16x32_bf16 v[120:123], v[230:233], v[148:151], v[120:123]
	s_waitcnt lgkmcnt(5)
	v_mfma_f32_16x16x32_bf16 v[52:55], v[234:237], v[136:139], v[52:55]
	v_mfma_f32_16x16x32_bf16 v[116:119], v[234:237], v[152:155], v[116:119]
	s_waitcnt lgkmcnt(4)
	v_mfma_f32_16x16x32_bf16 v[56:59], v[238:241], v[136:139], v[56:59]
	v_mfma_f32_16x16x32_bf16 v[120:123], v[238:241], v[152:155], v[120:123]
	s_waitcnt lgkmcnt(3)
	v_mfma_f32_16x16x32_bf16 v[60:63], v[196:199], v[132:135], v[60:63]
	v_mfma_f32_16x16x32_bf16 v[124:127], v[196:199], v[148:151], v[124:127]
	s_waitcnt lgkmcnt(2)
	v_mfma_f32_16x16x32_bf16 v[64:67], v[200:203], v[132:135], v[64:67]
	v_mfma_f32_16x16x32_bf16 v[128:131], v[200:203], v[148:151], v[128:131]
	s_waitcnt lgkmcnt(1)
	v_mfma_f32_16x16x32_bf16 v[60:63], v[204:207], v[136:139], v[60:63]
	v_mfma_f32_16x16x32_bf16 v[124:127], v[204:207], v[152:155], v[124:127]
	s_waitcnt lgkmcnt(0)
	v_mfma_f32_16x16x32_bf16 v[64:67], v[220:223], v[136:139], v[64:67]
	v_mfma_f32_16x16x32_bf16 v[128:131], v[220:223], v[152:155], v[128:131]
	v_add_u32_e32 v246, 0x100, v246
	v_add_u32_e32 v247, 0x100, v247
	global_load_dwordx4 v[132:135], v246, s[92:93] offset:0
	global_load_dwordx4 v[136:139], v246, s[92:93] offset:64
	global_load_dwordx4 v[148:151], v247, s[92:93] offset:0
	global_load_dwordx4 v[152:155], v247, s[92:93] offset:64
	ds_read_b128 v[196:199], v209
	ds_read_b128 v[200:203], v209 offset:4096
	ds_read_b128 v[204:207], v210
	ds_read_b128 v[220:223], v210 offset:4096
	ds_read_b128 v[230:233], v209 offset:8192
	ds_read_b128 v[234:237], v209 offset:12288
	ds_read_b128 v[238:241], v210 offset:8192
	s_waitcnt vmcnt(12) lgkmcnt(6)
	v_mfma_f32_16x16x32_bf16 v[4:7], v[196:199], v[140:143], v[4:7]
	v_mfma_f32_16x16x32_bf16 v[68:71], v[196:199], v[156:159], v[68:71]
	ds_read_b128 v[196:199], v210 offset:12288
	s_waitcnt lgkmcnt(6)
	v_mfma_f32_16x16x32_bf16 v[8:11], v[200:203], v[140:143], v[8:11]
	v_mfma_f32_16x16x32_bf16 v[72:75], v[200:203], v[156:159], v[72:75]
	ds_read_b128 v[200:203], v209 offset:16384
	s_waitcnt lgkmcnt(6)
	v_mfma_f32_16x16x32_bf16 v[4:7], v[204:207], v[144:147], v[4:7]
	v_mfma_f32_16x16x32_bf16 v[68:71], v[204:207], v[160:163], v[68:71]
	ds_read_b128 v[204:207], v209 offset:20480
	s_waitcnt lgkmcnt(6)
	v_mfma_f32_16x16x32_bf16 v[8:11], v[220:223], v[144:147], v[8:11]
	v_mfma_f32_16x16x32_bf16 v[72:75], v[220:223], v[160:163], v[72:75]
	ds_read_b128 v[220:223], v210 offset:16384
	s_waitcnt lgkmcnt(6)
	v_mfma_f32_16x16x32_bf16 v[12:15], v[230:233], v[140:143], v[12:15]
	v_mfma_f32_16x16x32_bf16 v[76:79], v[230:233], v[156:159], v[76:79]
	ds_read_b128 v[230:233], v210 offset:20480
	s_waitcnt lgkmcnt(6)
	v_mfma_f32_16x16x32_bf16 v[16:19], v[234:237], v[140:143], v[16:19]
	v_mfma_f32_16x16x32_bf16 v[80:83], v[234:237], v[156:159], v[80:83]
	ds_read_b128 v[234:237], v209 offset:24576
	s_waitcnt lgkmcnt(6)
	v_mfma_f32_16x16x32_bf16 v[12:15], v[238:241], v[144:147], v[12:15]
	v_mfma_f32_16x16x32_bf16 v[76:79], v[238:241], v[160:163], v[76:79]
	ds_read_b128 v[238:241], v209 offset:28672
	s_waitcnt lgkmcnt(6)
	v_mfma_f32_16x16x32_bf16 v[16:19], v[196:199], v[144:147], v[16:19]
	v_mfma_f32_16x16x32_bf16 v[80:83], v[196:199], v[160:163], v[80:83]
	ds_read_b128 v[196:199], v210 offset:24576
	s_waitcnt lgkmcnt(6)
	v_mfma_f32_16x16x32_bf16 v[20:23], v[200:203], v[140:143], v[20:23]
	v_mfma_f32_16x16x32_bf16 v[84:87], v[200:203], v[156:159], v[84:87]
	ds_read_b128 v[200:203], v210 offset:28672
	s_waitcnt lgkmcnt(6)
	v_mfma_f32_16x16x32_bf16 v[24:27], v[204:207], v[140:143], v[24:27]
	v_mfma_f32_16x16x32_bf16 v[88:91], v[204:207], v[156:159], v[88:91]
	ds_read_b128 v[204:207], v209 offset:32768
	s_waitcnt lgkmcnt(6)
	v_mfma_f32_16x16x32_bf16 v[20:23], v[220:223], v[144:147], v[20:23]
	v_mfma_f32_16x16x32_bf16 v[84:87], v[220:223], v[160:163], v[84:87]
	ds_read_b128 v[220:223], v209 offset:36864
	s_waitcnt lgkmcnt(6)
	v_mfma_f32_16x16x32_bf16 v[24:27], v[230:233], v[144:147], v[24:27]
	v_mfma_f32_16x16x32_bf16 v[88:91], v[230:233], v[160:163], v[88:91]
	ds_read_b128 v[230:233], v210 offset:32768
	s_waitcnt lgkmcnt(6)
	v_mfma_f32_16x16x32_bf16 v[28:31], v[234:237], v[140:143], v[28:31]
	v_mfma_f32_16x16x32_bf16 v[92:95], v[234:237], v[156:159], v[92:95]
	ds_read_b128 v[234:237], v210 offset:36864
	s_waitcnt lgkmcnt(6)
	v_mfma_f32_16x16x32_bf16 v[32:35], v[238:241], v[140:143], v[32:35]
	v_mfma_f32_16x16x32_bf16 v[96:99], v[238:241], v[156:159], v[96:99]
	ds_read_b128 v[238:241], v209 offset:40960
	s_waitcnt lgkmcnt(6)
	v_mfma_f32_16x16x32_bf16 v[28:31], v[196:199], v[144:147], v[28:31]
	v_mfma_f32_16x16x32_bf16 v[92:95], v[196:199], v[160:163], v[92:95]
	ds_read_b128 v[196:199], v209 offset:45056
	s_waitcnt lgkmcnt(6)
; __device__ __forceinline__ f32x4 mfma16(bf16x8 a, bf16x8 b, f32x4 c) { return __builtin_amdgcn_mfma_f32_16x16x32_bf16(a, b, c, 0, 0, 0); }
; __device__ void cross_items(const Params& p, LAS unsigned char* lds) {
;     ...
;             for (int kt = 0; kt < 16; ++kt)
; #pragma unroll
;                 for (int ks = 0; ks < 4; ++ks) sc[kt] = mfma16(frag_row(buf, KV_STRIDE, 16 * kt, 32 * ks, idx, g), qf[ks], sc[kt]);
;         }
;         const float scl = 0.04419417382415922f * LOG2E;
;         float mx = -1e30f;
; #pragma unroll
;         for (int kt = 0; kt < 16; ++kt)
; #pragma unroll
;             for (int rr = 0; rr < 4; ++rr) { const float sv = sc[kt][rr] * scl; sc[kt][rr] = sv; mx = fmaxf(mx, sv); }
;         mx = fmaxf(mx, __shfl_xor(mx, 16)); mx = fmaxf(mx, __shfl_xor(mx, 32));
	v_mfma_f32_16x16x32_bf16 v[32:35], v[200:203], v[144:147], v[32:35]
	v_mfma_f32_16x16x32_bf16 v[96:99], v[200:203], v[160:163], v[96:99]
	ds_read_b128 v[200:203], v210 offset:40960
	s_waitcnt lgkmcnt(6)
	v_mfma_f32_16x16x32_bf16 v[36:39], v[204:207], v[140:143], v[36:39]
	v_mfma_f32_16x16x32_bf16 v[100:103], v[204:207], v[156:159], v[100:103]
	ds_read_b128 v[204:207], v210 offset:45056
	s_waitcnt lgkmcnt(6)
	v_mfma_f32_16x16x32_bf16 v[40:43], v[220:223], v[140:143], v[40:43]
	v_mfma_f32_16x16x32_bf16 v[104:107], v[220:223], v[156:159], v[104:107]
	ds_read_b128 v[220:223], v209 offset:49152
	s_waitcnt lgkmcnt(6)
	v_mfma_f32_16x16x32_bf16 v[36:39], v[230:233], v[144:147], v[36:39]
	v_mfma_f32_16x16x32_bf16 v[100:103], v[230:233], v[160:163], v[100:103]
	ds_read_b128 v[230:233], v209 offset:53248
	s_waitcnt lgkmcnt(6)
	v_mfma_f32_16x16x32_bf16 v[40:43], v[234:237], v[144:147], v[40:43]
	v_mfma_f32_16x16x32_bf16 v[104:107], v[234:237], v[160:163], v[104:107]
	ds_read_b128 v[234:237], v210 offset:49152
	s_waitcnt lgkmcnt(6)
	v_mfma_f32_16x16x32_bf16 v[44:47], v[238:241], v[140:143], v[44:47]
	v_mfma_f32_16x16x32_bf16 v[108:111], v[238:241], v[156:159], v[108:111]
	ds_read_b128 v[238:241], v210 offset:53248
	s_waitcnt lgkmcnt(6)
	v_mfma_f32_16x16x32_bf16 v[48:51], v[196:199], v[140:143], v[48:51]
	v_mfma_f32_16x16x32_bf16 v[112:115], v[196:199], v[156:159], v[112:115]
	ds_read_b128 v[196:199], v209 offset:57344
	s_waitcnt lgkmcnt(6)
	v_mfma_f32_16x16x32_bf16 v[44:47], v[200:203], v[144:147], v[44:47]
	v_mfma_f32_16x16x32_bf16 v[108:111], v[200:203], v[160:163], v[108:111]
	ds_read_b128 v[200:203], v209 offset:61440
	s_waitcnt lgkmcnt(6)
	v_mfma_f32_16x16x32_bf16 v[48:51], v[204:207], v[144:147], v[48:51]
	v_mfma_f32_16x16x32_bf16 v[112:115], v[204:207], v[160:163], v[112:115]
	ds_read_b128 v[204:207], v210 offset:57344
	s_waitcnt lgkmcnt(6)
	v_mfma_f32_16x16x32_bf16 v[52:55], v[220:223], v[140:143], v[52:55]
	v_mfma_f32_16x16x32_bf16 v[116:119], v[220:223], v[156:159], v[116:119]
	ds_read_b128 v[220:223], v210 offset:61440
	s_waitcnt lgkmcnt(6)
	v_mfma_f32_16x16x32_bf16 v[56:59], v[230:233], v[140:143], v[56:59]
	v_mfma_f32_16x16x32_bf16 v[120:123], v[230:233], v[156:159], v[120:123]
	s_waitcnt lgkmcnt(5)
	v_mfma_f32_16x16x32_bf16 v[52:55], v[234:237], v[144:147], v[52:55]
	v_mfma_f32_16x16x32_bf16 v[116:119], v[234:237], v[160:163], v[116:119]
	s_waitcnt lgkmcnt(4)
	v_mfma_f32_16x16x32_bf16 v[56:59], v[238:241], v[144:147], v[56:59]
	v_mfma_f32_16x16x32_bf16 v[120:123], v[238:241], v[160:163], v[120:123]
	s_waitcnt lgkmcnt(3)
	v_mfma_f32_16x16x32_bf16 v[60:63], v[196:199], v[140:143], v[60:63]
	v_mfma_f32_16x16x32_bf16 v[124:127], v[196:199], v[156:159], v[124:127]
	s_waitcnt lgkmcnt(2)
	v_mfma_f32_16x16x32_bf16 v[64:67], v[200:203], v[140:143], v[64:67]
	v_mfma_f32_16x16x32_bf16 v[128:131], v[200:203], v[156:159], v[128:131]
	s_waitcnt lgkmcnt(1)
	v_mfma_f32_16x16x32_bf16 v[60:63], v[204:207], v[144:147], v[60:63]
	v_mfma_f32_16x16x32_bf16 v[124:127], v[204:207], v[160:163], v[124:127]
	s_waitcnt lgkmcnt(0)
	v_mfma_f32_16x16x32_bf16 v[64:67], v[220:223], v[144:147], v[64:67]
	v_mfma_f32_16x16x32_bf16 v[128:131], v[220:223], v[160:163], v[128:131]
	global_load_dwordx4 v[140:143], v246, s[92:93] offset:128
	global_load_dwordx4 v[144:147], v246, s[92:93] offset:192
	global_load_dwordx4 v[156:159], v247, s[92:93] offset:128
	global_load_dwordx4 v[160:163], v247, s[92:93] offset:192
	v_xor_b32_e32 v2, 0x10000, v2
	v_xor_b32_e32 v208, 0x10000, v208
	v_xor_b32_e32 v209, 0x10000, v209
	v_xor_b32_e32 v210, 0x10000, v210
	s_add_i32 s4, s4, 1
	s_cmp_lt_u32 s4, 4
	s_cbranch_scc1 .Lxa_qk
	s_nop 7
	s_nop 7
	v_and_b32_e32 v199, 63, v212
	v_xor_b32_e32 v196, 16, v199
	v_lshlrev_b32_e32 v196, 2, v196
	v_xor_b32_e32 v197, 32, v199
	v_lshlrev_b32_e32 v197, 2, v197
	s_mov_b32 s5, 0x3d8293ee
	v_mov_b32_e32 v198, 0xf149f2ca
	v_mul_f32_e32 v199, 0x3d8293ee, v4
	v_mul_f32_e32 v200, 0x3d8293ee, v5
	v_max3_f32 v198, v198, v199, v200
	v_mul_f32_e32 v199, 0x3d8293ee, v6
	v_mul_f32_e32 v200, 0x3d8293ee, v7
	v_max3_f32 v198, v198, v199, v200
	v_mul_f32_e32 v199, 0x3d8293ee, v8
	v_mul_f32_e32 v200, 0x3d8293ee, v9
	v_max3_f32 v198, v198, v199, v200
	v_mul_f32_e32 v199, 0x3d8293ee, v10
	v_mul_f32_e32 v200, 0x3d8293ee, v11
	v_max3_f32 v198, v198, v199, v200
	v_mul_f32_e32 v199, 0x3d8293ee, v12
	v_mul_f32_e32 v200, 0x3d8293ee, v13
	v_max3_f32 v198, v198, v199, v200
	v_mul_f32_e32 v199, 0x3d8293ee, v14
	v_mul_f32_e32 v200, 0x3d8293ee, v15
	v_max3_f32 v198, v198, v199, v200
	v_mul_f32_e32 v199, 0x3d8293ee, v16
	v_mul_f32_e32 v200, 0x3d8293ee, v17
	v_max3_f32 v198, v198, v199, v200
	v_mul_f32_e32 v199, 0x3d8293ee, v18
	v_mul_f32_e32 v200, 0x3d8293ee, v19
	v_max3_f32 v198, v198, v199, v200
	v_mul_f32_e32 v199, 0x3d8293ee, v20
	v_mul_f32_e32 v200, 0x3d8293ee, v21
	v_max3_f32 v198, v198, v199, v200
	v_mul_f32_e32 v199, 0x3d8293ee, v22
	v_mul_f32_e32 v200, 0x3d8293ee, v23
	v_max3_f32 v198, v198, v199, v200
	v_mul_f32_e32 v199, 0x3d8293ee, v24
	v_mul_f32_e32 v200, 0x3d8293ee, v25
	v_max3_f32 v198, v198, v199, v200
	v_mul_f32_e32 v199, 0x3d8293ee, v26
	v_mul_f32_e32 v200, 0x3d8293ee, v27
	v_max3_f32 v198, v198, v199, v200
	v_mul_f32_e32 v199, 0x3d8293ee, v28
	v_mul_f32_e32 v200, 0x3d8293ee, v29
	v_max3_f32 v198, v198, v199, v200
	v_mul_f32_e32 v199, 0x3d8293ee, v30
	v_mul_f32_e32 v200, 0x3d8293ee, v31
	v_max3_f32 v198, v198, v199, v200
	v_mul_f32_e32 v199, 0x3d8293ee, v32
	v_mul_f32_e32 v200, 0x3d8293ee, v33
	v_max3_f32 v198, v198, v199, v200
	v_mul_f32_e32 v199, 0x3d8293ee, v34
	v_mul_f32_e32 v200, 0x3d8293ee, v35
	v_max3_f32 v198, v198, v199, v200
	v_mul_f32_e32 v199, 0x3d8293ee, v36
; __device__ __forceinline__ float fexp2(float x) { return __builtin_amdgcn_exp2f(x); }
; __device__ void cross_items(const Params& p, LAS unsigned char* lds) {
;     ...
;         const float scl = 0.04419417382415922f * LOG2E;
;         float mx = -1e30f;
; #pragma unroll
;         for (int kt = 0; kt < 16; ++kt)
; #pragma unroll
;             for (int rr = 0; rr < 4; ++rr) { const float sv = sc[kt][rr] * scl; sc[kt][rr] = sv; mx = fmaxf(mx, sv); }
;         mx = fmaxf(mx, __shfl_xor(mx, 16)); mx = fmaxf(mx, __shfl_xor(mx, 32));
;         float sum = 0.f;
; #pragma unroll
;         for (int kt = 0; kt < 16; ++kt)
; #pragma unroll
;             for (int rr = 0; rr < 4; ++rr) { const float e = fexp2(sc[kt][rr] - mx); sc[kt][rr] = e; sum += e; }
	v_mul_f32_e32 v200, 0x3d8293ee, v37
	v_max3_f32 v198, v198, v199, v200
	v_mul_f32_e32 v199, 0x3d8293ee, v38
	v_mul_f32_e32 v200, 0x3d8293ee, v39
	v_max3_f32 v198, v198, v199, v200
	v_mul_f32_e32 v199, 0x3d8293ee, v40
	v_mul_f32_e32 v200, 0x3d8293ee, v41
	v_max3_f32 v198, v198, v199, v200
	v_mul_f32_e32 v199, 0x3d8293ee, v42
	v_mul_f32_e32 v200, 0x3d8293ee, v43
	v_max3_f32 v198, v198, v199, v200
	v_mul_f32_e32 v199, 0x3d8293ee, v44
	v_mul_f32_e32 v200, 0x3d8293ee, v45
	v_max3_f32 v198, v198, v199, v200
	v_mul_f32_e32 v199, 0x3d8293ee, v46
	v_mul_f32_e32 v200, 0x3d8293ee, v47
	v_max3_f32 v198, v198, v199, v200
	v_mul_f32_e32 v199, 0x3d8293ee, v48
	v_mul_f32_e32 v200, 0x3d8293ee, v49
	v_max3_f32 v198, v198, v199, v200
	v_mul_f32_e32 v199, 0x3d8293ee, v50
	v_mul_f32_e32 v200, 0x3d8293ee, v51
	v_max3_f32 v198, v198, v199, v200
	v_mul_f32_e32 v199, 0x3d8293ee, v52
	v_mul_f32_e32 v200, 0x3d8293ee, v53
	v_max3_f32 v198, v198, v199, v200
	v_mul_f32_e32 v199, 0x3d8293ee, v54
	v_mul_f32_e32 v200, 0x3d8293ee, v55
	v_max3_f32 v198, v198, v199, v200
	v_mul_f32_e32 v199, 0x3d8293ee, v56
	v_mul_f32_e32 v200, 0x3d8293ee, v57
	v_max3_f32 v198, v198, v199, v200
	v_mul_f32_e32 v199, 0x3d8293ee, v58
	v_mul_f32_e32 v200, 0x3d8293ee, v59
	v_max3_f32 v198, v198, v199, v200
	v_mul_f32_e32 v199, 0x3d8293ee, v60
	v_mul_f32_e32 v200, 0x3d8293ee, v61
	v_max3_f32 v198, v198, v199, v200
	v_mul_f32_e32 v199, 0x3d8293ee, v62
	v_mul_f32_e32 v200, 0x3d8293ee, v63
	v_max3_f32 v198, v198, v199, v200
	v_mul_f32_e32 v199, 0x3d8293ee, v64
	v_mul_f32_e32 v200, 0x3d8293ee, v65
	v_max3_f32 v198, v198, v199, v200
	v_mul_f32_e32 v199, 0x3d8293ee, v66
	v_mul_f32_e32 v200, 0x3d8293ee, v67
	v_max3_f32 v198, v198, v199, v200
	ds_bpermute_b32 v199, v196, v198
	s_waitcnt lgkmcnt(0)
	v_max_f32_e32 v198, v198, v199
	ds_bpermute_b32 v199, v197, v198
	s_waitcnt lgkmcnt(0)
	v_max_f32_e32 v198, v198, v199
	v_fma_f32 v4, v4, s5, -v198
	v_fma_f32 v5, v5, s5, -v198
	v_fma_f32 v6, v6, s5, -v198
	v_fma_f32 v7, v7, s5, -v198
	v_fma_f32 v8, v8, s5, -v198
	v_fma_f32 v9, v9, s5, -v198
	v_fma_f32 v10, v10, s5, -v198
	v_fma_f32 v11, v11, s5, -v198
	v_fma_f32 v12, v12, s5, -v198
	v_fma_f32 v13, v13, s5, -v198
	v_fma_f32 v14, v14, s5, -v198
	v_fma_f32 v15, v15, s5, -v198
	v_fma_f32 v16, v16, s5, -v198
	v_fma_f32 v17, v17, s5, -v198
	v_fma_f32 v18, v18, s5, -v198
	v_fma_f32 v19, v19, s5, -v198
	v_fma_f32 v20, v20, s5, -v198
	v_fma_f32 v21, v21, s5, -v198
	v_fma_f32 v22, v22, s5, -v198
	v_fma_f32 v23, v23, s5, -v198
	v_fma_f32 v24, v24, s5, -v198
	v_fma_f32 v25, v25, s5, -v198
	v_fma_f32 v26, v26, s5, -v198
	v_fma_f32 v27, v27, s5, -v198
	v_fma_f32 v28, v28, s5, -v198
	v_fma_f32 v29, v29, s5, -v198
	v_fma_f32 v30, v30, s5, -v198
	v_fma_f32 v31, v31, s5, -v198
	v_fma_f32 v32, v32, s5, -v198
	v_fma_f32 v33, v33, s5, -v198
	v_fma_f32 v34, v34, s5, -v198
	v_fma_f32 v35, v35, s5, -v198
	v_fma_f32 v36, v36, s5, -v198
	v_fma_f32 v37, v37, s5, -v198
	v_fma_f32 v38, v38, s5, -v198
	v_fma_f32 v39, v39, s5, -v198
	v_fma_f32 v40, v40, s5, -v198
	v_fma_f32 v41, v41, s5, -v198
	v_fma_f32 v42, v42, s5, -v198
	v_fma_f32 v43, v43, s5, -v198
	v_fma_f32 v44, v44, s5, -v198
	v_fma_f32 v45, v45, s5, -v198
	v_fma_f32 v46, v46, s5, -v198
	v_fma_f32 v47, v47, s5, -v198
	v_fma_f32 v48, v48, s5, -v198
	v_fma_f32 v49, v49, s5, -v198
	v_fma_f32 v50, v50, s5, -v198
	v_fma_f32 v51, v51, s5, -v198
	v_fma_f32 v52, v52, s5, -v198
	v_fma_f32 v53, v53, s5, -v198
	v_fma_f32 v54, v54, s5, -v198
	v_fma_f32 v55, v55, s5, -v198
	v_fma_f32 v56, v56, s5, -v198
	v_fma_f32 v57, v57, s5, -v198
	v_fma_f32 v58, v58, s5, -v198
	v_fma_f32 v59, v59, s5, -v198
	v_fma_f32 v60, v60, s5, -v198
	v_fma_f32 v61, v61, s5, -v198
	v_fma_f32 v62, v62, s5, -v198
	v_fma_f32 v63, v63, s5, -v198
	v_fma_f32 v64, v64, s5, -v198
	v_fma_f32 v65, v65, s5, -v198
	v_fma_f32 v66, v66, s5, -v198
	v_fma_f32 v67, v67, s5, -v198
	v_exp_f32_e32 v4, v4
	v_exp_f32_e32 v5, v5
	v_exp_f32_e32 v6, v6
	v_exp_f32_e32 v7, v7
	v_exp_f32_e32 v8, v8
	v_exp_f32_e32 v9, v9
	v_exp_f32_e32 v10, v10
	v_exp_f32_e32 v11, v11
	v_exp_f32_e32 v12, v12
	v_exp_f32_e32 v13, v13
	v_exp_f32_e32 v14, v14
	v_exp_f32_e32 v15, v15
	v_exp_f32_e32 v16, v16
	v_exp_f32_e32 v17, v17
	v_exp_f32_e32 v18, v18
	v_exp_f32_e32 v19, v19
	v_exp_f32_e32 v20, v20
	v_exp_f32_e32 v21, v21
	v_exp_f32_e32 v22, v22
	v_exp_f32_e32 v23, v23
	v_exp_f32_e32 v24, v24
	v_exp_f32_e32 v25, v25
	v_exp_f32_e32 v26, v26
	v_exp_f32_e32 v27, v27
	v_exp_f32_e32 v28, v28
	v_exp_f32_e32 v29, v29
	v_exp_f32_e32 v30, v30
	v_exp_f32_e32 v31, v31
	v_exp_f32_e32 v32, v32
	v_exp_f32_e32 v33, v33
	v_exp_f32_e32 v34, v34
	v_exp_f32_e32 v35, v35
	v_exp_f32_e32 v36, v36
	v_exp_f32_e32 v37, v37
	v_exp_f32_e32 v38, v38
	v_exp_f32_e32 v39, v39
	v_exp_f32_e32 v40, v40
	v_exp_f32_e32 v41, v41
	v_exp_f32_e32 v42, v42
	v_exp_f32_e32 v43, v43
	v_exp_f32_e32 v44, v44
	v_exp_f32_e32 v45, v45
	v_exp_f32_e32 v46, v46
	v_exp_f32_e32 v47, v47
	v_exp_f32_e32 v48, v48
	v_exp_f32_e32 v49, v49
	v_exp_f32_e32 v50, v50
	v_exp_f32_e32 v51, v51
	v_exp_f32_e32 v52, v52
	v_exp_f32_e32 v53, v53
	v_exp_f32_e32 v54, v54
	v_exp_f32_e32 v55, v55
	v_exp_f32_e32 v56, v56
	v_exp_f32_e32 v57, v57
	v_exp_f32_e32 v58, v58
	v_exp_f32_e32 v59, v59
	v_exp_f32_e32 v60, v60
	v_exp_f32_e32 v61, v61
	v_exp_f32_e32 v62, v62
	v_exp_f32_e32 v63, v63
	v_exp_f32_e32 v64, v64
	v_exp_f32_e32 v65, v65
	v_exp_f32_e32 v66, v66
	v_exp_f32_e32 v67, v67
	s_nop 0
	v_add_f32_e32 v201, 0, v4
	v_add_f32_e32 v201, v5, v201
	v_add_f32_e32 v201, v6, v201
	v_add_f32_e32 v201, v7, v201
	v_add_f32_e32 v201, v8, v201
	v_add_f32_e32 v201, v9, v201
	v_add_f32_e32 v201, v10, v201
	v_add_f32_e32 v201, v11, v201
; __device__ __forceinline__ unsigned cvt_pk_bf16(float lo, float hi) { const f32x2v v = {lo, hi}; const b16x2v r = __builtin_convertvector(v, b16x2v); return __builtin_bit_cast(unsigned, r); }
; __device__ __forceinline__ float fexp2(float x) { return __builtin_amdgcn_exp2f(x); }
; __device__ void cross_items(const Params& p, LAS unsigned char* lds) {
;     ...
; #pragma unroll
;         for (int kt = 0; kt < 16; ++kt)
; #pragma unroll
;             for (int rr = 0; rr < 4; ++rr) { const float e = fexp2(sc[kt][rr] - mx); sc[kt][rr] = e; sum += e; }
;         sum += __shfl_xor(sum, 16); sum += __shfl_xor(sum, 32);
;         const float inv = 1.0f / sum;
;         bf16x8 pf[8];
; #pragma unroll
;         for (int sx = 0; sx < 8; ++sx) { u32x4 pw; pw.x = cvt_pk_bf16(sc[2 * sx][0], sc[2 * sx][1]); pw.y = cvt_pk_bf16(sc[2 * sx][2], sc[2 * sx][3]); pw.z = cvt_pk_bf16(sc[2 * sx + 1][0], sc[2 * sx + 1][1]); pw.w = cvt_pk_bf16(sc[2 * sx + 1][2], sc[2 * sx + 1][3]);
;             pf[sx] = __builtin_bit_cast(bf16x8, pw); }
	v_add_f32_e32 v201, v12, v201
	v_add_f32_e32 v201, v13, v201
	v_add_f32_e32 v201, v14, v201
	v_add_f32_e32 v201, v15, v201
	v_add_f32_e32 v201, v16, v201
	v_add_f32_e32 v201, v17, v201
	v_add_f32_e32 v201, v18, v201
	v_add_f32_e32 v201, v19, v201
	v_add_f32_e32 v201, v20, v201
	v_add_f32_e32 v201, v21, v201
	v_add_f32_e32 v201, v22, v201
	v_add_f32_e32 v201, v23, v201
	v_add_f32_e32 v201, v24, v201
	v_add_f32_e32 v201, v25, v201
	v_add_f32_e32 v201, v26, v201
	v_add_f32_e32 v201, v27, v201
	v_add_f32_e32 v201, v28, v201
	v_add_f32_e32 v201, v29, v201
	v_add_f32_e32 v201, v30, v201
	v_add_f32_e32 v201, v31, v201
	v_add_f32_e32 v201, v32, v201
	v_add_f32_e32 v201, v33, v201
	v_add_f32_e32 v201, v34, v201
	v_add_f32_e32 v201, v35, v201
	v_add_f32_e32 v201, v36, v201
	v_add_f32_e32 v201, v37, v201
	v_add_f32_e32 v201, v38, v201
	v_add_f32_e32 v201, v39, v201
	v_add_f32_e32 v201, v40, v201
	v_add_f32_e32 v201, v41, v201
	v_add_f32_e32 v201, v42, v201
	v_add_f32_e32 v201, v43, v201
	v_add_f32_e32 v201, v44, v201
	v_add_f32_e32 v201, v45, v201
	v_add_f32_e32 v201, v46, v201
	v_add_f32_e32 v201, v47, v201
	v_add_f32_e32 v201, v48, v201
	v_add_f32_e32 v201, v49, v201
	v_add_f32_e32 v201, v50, v201
	v_add_f32_e32 v201, v51, v201
	v_add_f32_e32 v201, v52, v201
	v_add_f32_e32 v201, v53, v201
	v_add_f32_e32 v201, v54, v201
	v_add_f32_e32 v201, v55, v201
	v_add_f32_e32 v201, v56, v201
	v_add_f32_e32 v201, v57, v201
	v_add_f32_e32 v201, v58, v201
	v_add_f32_e32 v201, v59, v201
	v_add_f32_e32 v201, v60, v201
	v_add_f32_e32 v201, v61, v201
	v_add_f32_e32 v201, v62, v201
	v_add_f32_e32 v201, v63, v201
	v_add_f32_e32 v201, v64, v201
	v_add_f32_e32 v201, v65, v201
	v_add_f32_e32 v201, v66, v201
	v_add_f32_e32 v201, v67, v201
	ds_bpermute_b32 v199, v196, v201
	s_waitcnt lgkmcnt(0)
	v_add_f32_e32 v201, v201, v199
	ds_bpermute_b32 v199, v197, v201
	s_waitcnt lgkmcnt(0)
	v_add_f32_e32 v201, v201, v199
	v_div_scale_f32 v199, s[6:7], v201, v201, 1.0
	v_rcp_f32_e32 v200, v199
	s_nop 0
	v_fma_f32 v244, -v199, v200, 1.0
	v_fmac_f32_e32 v200, v244, v200
	v_div_scale_f32 v244, vcc, 1.0, v201, 1.0
	v_mul_f32_e32 v202, v244, v200
	v_fma_f32 v203, -v199, v202, v244
	v_fmac_f32_e32 v202, v203, v200
	v_fma_f32 v199, -v199, v202, v244
	s_nop 1
	v_div_fmas_f32 v199, v199, v200, v202
	v_div_fixup_f32 v244, v199, v201, 1.0
	v_cvt_pk_bf16_f32 v4, v4, v5
	v_cvt_pk_bf16_f32 v5, v6, v7
	v_cvt_pk_bf16_f32 v6, v8, v9
	v_cvt_pk_bf16_f32 v7, v10, v11
	v_cvt_pk_bf16_f32 v12, v12, v13
	v_cvt_pk_bf16_f32 v13, v14, v15
	v_cvt_pk_bf16_f32 v14, v16, v17
	v_cvt_pk_bf16_f32 v15, v18, v19
	v_cvt_pk_bf16_f32 v20, v20, v21
	v_cvt_pk_bf16_f32 v21, v22, v23
	v_cvt_pk_bf16_f32 v22, v24, v25
	v_cvt_pk_bf16_f32 v23, v26, v27
	v_cvt_pk_bf16_f32 v28, v28, v29
	v_cvt_pk_bf16_f32 v29, v30, v31
	v_cvt_pk_bf16_f32 v30, v32, v33
	v_cvt_pk_bf16_f32 v31, v34, v35
	v_cvt_pk_bf16_f32 v36, v36, v37
	v_cvt_pk_bf16_f32 v37, v38, v39
	v_cvt_pk_bf16_f32 v38, v40, v41
	v_cvt_pk_bf16_f32 v39, v42, v43
	v_cvt_pk_bf16_f32 v44, v44, v45
	v_cvt_pk_bf16_f32 v45, v46, v47
	v_cvt_pk_bf16_f32 v46, v48, v49
	v_cvt_pk_bf16_f32 v47, v50, v51
	v_cvt_pk_bf16_f32 v52, v52, v53
	v_cvt_pk_bf16_f32 v53, v54, v55
	v_cvt_pk_bf16_f32 v54, v56, v57
	v_cvt_pk_bf16_f32 v55, v58, v59
	v_cvt_pk_bf16_f32 v60, v60, v61
	v_cvt_pk_bf16_f32 v61, v62, v63
	v_cvt_pk_bf16_f32 v62, v64, v65
	v_cvt_pk_bf16_f32 v63, v66, v67
	v_mov_b32_e32 v198, 0xf149f2ca
	v_mul_f32_e32 v199, 0x3d8293ee, v68
	v_mul_f32_e32 v200, 0x3d8293ee, v69
	v_max3_f32 v198, v198, v199, v200
	v_mul_f32_e32 v199, 0x3d8293ee, v70
	v_mul_f32_e32 v200, 0x3d8293ee, v71
	v_max3_f32 v198, v198, v199, v200
	v_mul_f32_e32 v199, 0x3d8293ee, v72
	v_mul_f32_e32 v200, 0x3d8293ee, v73
	v_max3_f32 v198, v198, v199, v200
	v_mul_f32_e32 v199, 0x3d8293ee, v74
	v_mul_f32_e32 v200, 0x3d8293ee, v75
	v_max3_f32 v198, v198, v199, v200
	v_mul_f32_e32 v199, 0x3d8293ee, v76
	v_mul_f32_e32 v200, 0x3d8293ee, v77
	v_max3_f32 v198, v198, v199, v200
	v_mul_f32_e32 v199, 0x3d8293ee, v78
	v_mul_f32_e32 v200, 0x3d8293ee, v79
	v_max3_f32 v198, v198, v199, v200
	v_mul_f32_e32 v199, 0x3d8293ee, v80
	v_mul_f32_e32 v200, 0x3d8293ee, v81
	v_max3_f32 v198, v198, v199, v200
	v_mul_f32_e32 v199, 0x3d8293ee, v82
	v_mul_f32_e32 v200, 0x3d8293ee, v83
	v_max3_f32 v198, v198, v199, v200
	v_mul_f32_e32 v199, 0x3d8293ee, v84
	v_mul_f32_e32 v200, 0x3d8293ee, v85
	v_max3_f32 v198, v198, v199, v200
	v_mul_f32_e32 v199, 0x3d8293ee, v86
	v_mul_f32_e32 v200, 0x3d8293ee, v87
	v_max3_f32 v198, v198, v199, v200
	v_mul_f32_e32 v199, 0x3d8293ee, v88
	v_mul_f32_e32 v200, 0x3d8293ee, v89
	v_max3_f32 v198, v198, v199, v200
	v_mul_f32_e32 v199, 0x3d8293ee, v90
	v_mul_f32_e32 v200, 0x3d8293ee, v91
	v_max3_f32 v198, v198, v199, v200
	v_mul_f32_e32 v199, 0x3d8293ee, v92
	v_mul_f32_e32 v200, 0x3d8293ee, v93
	v_max3_f32 v198, v198, v199, v200
	v_mul_f32_e32 v199, 0x3d8293ee, v94
	v_mul_f32_e32 v200, 0x3d8293ee, v95
	v_max3_f32 v198, v198, v199, v200
	v_mul_f32_e32 v199, 0x3d8293ee, v96
	v_mul_f32_e32 v200, 0x3d8293ee, v97
	v_max3_f32 v198, v198, v199, v200
	v_mul_f32_e32 v199, 0x3d8293ee, v98
	v_mul_f32_e32 v200, 0x3d8293ee, v99
	v_max3_f32 v198, v198, v199, v200
	v_mul_f32_e32 v199, 0x3d8293ee, v100
	v_mul_f32_e32 v200, 0x3d8293ee, v101
	v_max3_f32 v198, v198, v199, v200
	v_mul_f32_e32 v199, 0x3d8293ee, v102
	v_mul_f32_e32 v200, 0x3d8293ee, v103
	v_max3_f32 v198, v198, v199, v200
	v_mul_f32_e32 v199, 0x3d8293ee, v104
	v_mul_f32_e32 v200, 0x3d8293ee, v105
	v_max3_f32 v198, v198, v199, v200
	v_mul_f32_e32 v199, 0x3d8293ee, v106
	v_mul_f32_e32 v200, 0x3d8293ee, v107
	v_max3_f32 v198, v198, v199, v200
	v_mul_f32_e32 v199, 0x3d8293ee, v108
	v_mul_f32_e32 v200, 0x3d8293ee, v109
	v_max3_f32 v198, v198, v199, v200
	v_mul_f32_e32 v199, 0x3d8293ee, v110
	v_mul_f32_e32 v200, 0x3d8293ee, v111
	v_max3_f32 v198, v198, v199, v200
	v_mul_f32_e32 v199, 0x3d8293ee, v112
	v_mul_f32_e32 v200, 0x3d8293ee, v113
	v_max3_f32 v198, v198, v199, v200
	v_mul_f32_e32 v199, 0x3d8293ee, v114
	v_mul_f32_e32 v200, 0x3d8293ee, v115
	v_max3_f32 v198, v198, v199, v200
	v_mul_f32_e32 v199, 0x3d8293ee, v116
	v_mul_f32_e32 v200, 0x3d8293ee, v117
	v_max3_f32 v198, v198, v199, v200
	v_mul_f32_e32 v199, 0x3d8293ee, v118
	v_mul_f32_e32 v200, 0x3d8293ee, v119
	v_max3_f32 v198, v198, v199, v200
	v_mul_f32_e32 v199, 0x3d8293ee, v120
	v_mul_f32_e32 v200, 0x3d8293ee, v121
	v_max3_f32 v198, v198, v199, v200
	v_mul_f32_e32 v199, 0x3d8293ee, v122
	v_mul_f32_e32 v200, 0x3d8293ee, v123
	v_max3_f32 v198, v198, v199, v200
	v_mul_f32_e32 v199, 0x3d8293ee, v124
	v_mul_f32_e32 v200, 0x3d8293ee, v125
	v_max3_f32 v198, v198, v199, v200
	v_mul_f32_e32 v199, 0x3d8293ee, v126
	v_mul_f32_e32 v200, 0x3d8293ee, v127
	v_max3_f32 v198, v198, v199, v200
	v_mul_f32_e32 v199, 0x3d8293ee, v128
	v_mul_f32_e32 v200, 0x3d8293ee, v129
	v_max3_f32 v198, v198, v199, v200
	v_mul_f32_e32 v199, 0x3d8293ee, v130
	v_mul_f32_e32 v200, 0x3d8293ee, v131
	v_max3_f32 v198, v198, v199, v200
	ds_bpermute_b32 v199, v196, v198
	s_waitcnt lgkmcnt(0)
; __device__ __forceinline__ float fexp2(float x) { return __builtin_amdgcn_exp2f(x); }
; __device__ void cross_items(const Params& p, LAS unsigned char* lds) {
;     ...
;         const float scl = 0.04419417382415922f * LOG2E;
;         float mx = -1e30f;
; #pragma unroll
;         for (int kt = 0; kt < 16; ++kt)
; #pragma unroll
;             for (int rr = 0; rr < 4; ++rr) { const float sv = sc[kt][rr] * scl; sc[kt][rr] = sv; mx = fmaxf(mx, sv); }
;         mx = fmaxf(mx, __shfl_xor(mx, 16)); mx = fmaxf(mx, __shfl_xor(mx, 32));
;         float sum = 0.f;
; #pragma unroll
;         for (int kt = 0; kt < 16; ++kt)
; #pragma unroll
;             for (int rr = 0; rr < 4; ++rr) { const float e = fexp2(sc[kt][rr] - mx); sc[kt][rr] = e; sum += e; }
;         sum += __shfl_xor(sum, 16); sum += __shfl_xor(sum, 32);
	v_max_f32_e32 v198, v198, v199
	ds_bpermute_b32 v199, v197, v198
	s_waitcnt lgkmcnt(0)
	v_max_f32_e32 v198, v198, v199
	v_fma_f32 v68, v68, s5, -v198
	v_fma_f32 v69, v69, s5, -v198
	v_fma_f32 v70, v70, s5, -v198
	v_fma_f32 v71, v71, s5, -v198
	v_fma_f32 v72, v72, s5, -v198
	v_fma_f32 v73, v73, s5, -v198
	v_fma_f32 v74, v74, s5, -v198
	v_fma_f32 v75, v75, s5, -v198
	v_fma_f32 v76, v76, s5, -v198
	v_fma_f32 v77, v77, s5, -v198
	v_fma_f32 v78, v78, s5, -v198
	v_fma_f32 v79, v79, s5, -v198
	v_fma_f32 v80, v80, s5, -v198
	v_fma_f32 v81, v81, s5, -v198
	v_fma_f32 v82, v82, s5, -v198
	v_fma_f32 v83, v83, s5, -v198
	v_fma_f32 v84, v84, s5, -v198
	v_fma_f32 v85, v85, s5, -v198
	v_fma_f32 v86, v86, s5, -v198
	v_fma_f32 v87, v87, s5, -v198
	v_fma_f32 v88, v88, s5, -v198
	v_fma_f32 v89, v89, s5, -v198
	v_fma_f32 v90, v90, s5, -v198
	v_fma_f32 v91, v91, s5, -v198
	v_fma_f32 v92, v92, s5, -v198
	v_fma_f32 v93, v93, s5, -v198
	v_fma_f32 v94, v94, s5, -v198
	v_fma_f32 v95, v95, s5, -v198
	v_fma_f32 v96, v96, s5, -v198
	v_fma_f32 v97, v97, s5, -v198
	v_fma_f32 v98, v98, s5, -v198
	v_fma_f32 v99, v99, s5, -v198
	v_fma_f32 v100, v100, s5, -v198
	v_fma_f32 v101, v101, s5, -v198
	v_fma_f32 v102, v102, s5, -v198
	v_fma_f32 v103, v103, s5, -v198
	v_fma_f32 v104, v104, s5, -v198
	v_fma_f32 v105, v105, s5, -v198
	v_fma_f32 v106, v106, s5, -v198
	v_fma_f32 v107, v107, s5, -v198
	v_fma_f32 v108, v108, s5, -v198
	v_fma_f32 v109, v109, s5, -v198
	v_fma_f32 v110, v110, s5, -v198
	v_fma_f32 v111, v111, s5, -v198
	v_fma_f32 v112, v112, s5, -v198
	v_fma_f32 v113, v113, s5, -v198
	v_fma_f32 v114, v114, s5, -v198
	v_fma_f32 v115, v115, s5, -v198
	v_fma_f32 v116, v116, s5, -v198
	v_fma_f32 v117, v117, s5, -v198
	v_fma_f32 v118, v118, s5, -v198
	v_fma_f32 v119, v119, s5, -v198
	v_fma_f32 v120, v120, s5, -v198
	v_fma_f32 v121, v121, s5, -v198
	v_fma_f32 v122, v122, s5, -v198
	v_fma_f32 v123, v123, s5, -v198
	v_fma_f32 v124, v124, s5, -v198
	v_fma_f32 v125, v125, s5, -v198
	v_fma_f32 v126, v126, s5, -v198
	v_fma_f32 v127, v127, s5, -v198
	v_fma_f32 v128, v128, s5, -v198
	v_fma_f32 v129, v129, s5, -v198
	v_fma_f32 v130, v130, s5, -v198
	v_fma_f32 v131, v131, s5, -v198
	v_exp_f32_e32 v68, v68
	v_exp_f32_e32 v69, v69
	v_exp_f32_e32 v70, v70
	v_exp_f32_e32 v71, v71
	v_exp_f32_e32 v72, v72
	v_exp_f32_e32 v73, v73
	v_exp_f32_e32 v74, v74
	v_exp_f32_e32 v75, v75
	v_exp_f32_e32 v76, v76
	v_exp_f32_e32 v77, v77
	v_exp_f32_e32 v78, v78
	v_exp_f32_e32 v79, v79
	v_exp_f32_e32 v80, v80
	v_exp_f32_e32 v81, v81
	v_exp_f32_e32 v82, v82
	v_exp_f32_e32 v83, v83
	v_exp_f32_e32 v84, v84
	v_exp_f32_e32 v85, v85
	v_exp_f32_e32 v86, v86
	v_exp_f32_e32 v87, v87
	v_exp_f32_e32 v88, v88
	v_exp_f32_e32 v89, v89
	v_exp_f32_e32 v90, v90
	v_exp_f32_e32 v91, v91
	v_exp_f32_e32 v92, v92
	v_exp_f32_e32 v93, v93
	v_exp_f32_e32 v94, v94
	v_exp_f32_e32 v95, v95
	v_exp_f32_e32 v96, v96
	v_exp_f32_e32 v97, v97
	v_exp_f32_e32 v98, v98
	v_exp_f32_e32 v99, v99
	v_exp_f32_e32 v100, v100
	v_exp_f32_e32 v101, v101
	v_exp_f32_e32 v102, v102
	v_exp_f32_e32 v103, v103
	v_exp_f32_e32 v104, v104
	v_exp_f32_e32 v105, v105
	v_exp_f32_e32 v106, v106
	v_exp_f32_e32 v107, v107
	v_exp_f32_e32 v108, v108
	v_exp_f32_e32 v109, v109
	v_exp_f32_e32 v110, v110
	v_exp_f32_e32 v111, v111
	v_exp_f32_e32 v112, v112
	v_exp_f32_e32 v113, v113
	v_exp_f32_e32 v114, v114
	v_exp_f32_e32 v115, v115
	v_exp_f32_e32 v116, v116
	v_exp_f32_e32 v117, v117
	v_exp_f32_e32 v118, v118
	v_exp_f32_e32 v119, v119
	v_exp_f32_e32 v120, v120
	v_exp_f32_e32 v121, v121
	v_exp_f32_e32 v122, v122
	v_exp_f32_e32 v123, v123
	v_exp_f32_e32 v124, v124
	v_exp_f32_e32 v125, v125
	v_exp_f32_e32 v126, v126
	v_exp_f32_e32 v127, v127
	v_exp_f32_e32 v128, v128
	v_exp_f32_e32 v129, v129
	v_exp_f32_e32 v130, v130
	v_exp_f32_e32 v131, v131
	s_nop 0
	v_add_f32_e32 v201, 0, v68
	v_add_f32_e32 v201, v69, v201
	v_add_f32_e32 v201, v70, v201
	v_add_f32_e32 v201, v71, v201
	v_add_f32_e32 v201, v72, v201
	v_add_f32_e32 v201, v73, v201
	v_add_f32_e32 v201, v74, v201
	v_add_f32_e32 v201, v75, v201
	v_add_f32_e32 v201, v76, v201
	v_add_f32_e32 v201, v77, v201
	v_add_f32_e32 v201, v78, v201
	v_add_f32_e32 v201, v79, v201
	v_add_f32_e32 v201, v80, v201
	v_add_f32_e32 v201, v81, v201
	v_add_f32_e32 v201, v82, v201
	v_add_f32_e32 v201, v83, v201
	v_add_f32_e32 v201, v84, v201
	v_add_f32_e32 v201, v85, v201
	v_add_f32_e32 v201, v86, v201
	v_add_f32_e32 v201, v87, v201
	v_add_f32_e32 v201, v88, v201
	v_add_f32_e32 v201, v89, v201
	v_add_f32_e32 v201, v90, v201
	v_add_f32_e32 v201, v91, v201
	v_add_f32_e32 v201, v92, v201
	v_add_f32_e32 v201, v93, v201
	v_add_f32_e32 v201, v94, v201
	v_add_f32_e32 v201, v95, v201
	v_add_f32_e32 v201, v96, v201
	v_add_f32_e32 v201, v97, v201
	v_add_f32_e32 v201, v98, v201
	v_add_f32_e32 v201, v99, v201
	v_add_f32_e32 v201, v100, v201
	v_add_f32_e32 v201, v101, v201
	v_add_f32_e32 v201, v102, v201
	v_add_f32_e32 v201, v103, v201
	v_add_f32_e32 v201, v104, v201
	v_add_f32_e32 v201, v105, v201
	v_add_f32_e32 v201, v106, v201
	v_add_f32_e32 v201, v107, v201
	v_add_f32_e32 v201, v108, v201
	v_add_f32_e32 v201, v109, v201
	v_add_f32_e32 v201, v110, v201
	v_add_f32_e32 v201, v111, v201
	v_add_f32_e32 v201, v112, v201
	v_add_f32_e32 v201, v113, v201
	v_add_f32_e32 v201, v114, v201
	v_add_f32_e32 v201, v115, v201
	v_add_f32_e32 v201, v116, v201
	v_add_f32_e32 v201, v117, v201
	v_add_f32_e32 v201, v118, v201
	v_add_f32_e32 v201, v119, v201
	v_add_f32_e32 v201, v120, v201
	v_add_f32_e32 v201, v121, v201
	v_add_f32_e32 v201, v122, v201
	v_add_f32_e32 v201, v123, v201
	v_add_f32_e32 v201, v124, v201
	v_add_f32_e32 v201, v125, v201
	v_add_f32_e32 v201, v126, v201
	v_add_f32_e32 v201, v127, v201
	v_add_f32_e32 v201, v128, v201
	v_add_f32_e32 v201, v129, v201
	v_add_f32_e32 v201, v130, v201
	v_add_f32_e32 v201, v131, v201
	ds_bpermute_b32 v199, v196, v201
	s_waitcnt lgkmcnt(0)
; #define LAS __attribute__((address_space(3)))
; __device__ __forceinline__ unsigned cvt_pk_bf16(float lo, float hi) { const f32x2v v = {lo, hi}; const b16x2v r = __builtin_convertvector(v, b16x2v); return __builtin_bit_cast(unsigned, r); }
; __device__ __forceinline__ f32x4 mfma16(bf16x8 a, bf16x8 b, f32x4 c) { return __builtin_amdgcn_mfma_f32_16x16x32_bf16(a, b, c, 0, 0, 0); }
; #define LDS_BARRIER() do { asm volatile("s_waitcnt lgkmcnt(0)" ::: "memory"); __builtin_amdgcn_s_barrier(); asm volatile("" ::: "memory"); } while (0)
; #define XSTORE(buf) do { _Pragma("unroll") for (int _it = 0; _it < 8; ++_it) *(LAS u32x4*)((buf) + (srow + 32 * _it) * KV_STRIDE + piece * 16) = pre[_it]; } while (0)
; __device__ void cross_items(const Params& p, LAS unsigned char* lds) {
;     ...
;         sum += __shfl_xor(sum, 16); sum += __shfl_xor(sum, 32);
;         const float inv = 1.0f / sum;
;         bf16x8 pf[8];
; #pragma unroll
;         for (int sx = 0; sx < 8; ++sx) { u32x4 pw; pw.x = cvt_pk_bf16(sc[2 * sx][0], sc[2 * sx][1]); pw.y = cvt_pk_bf16(sc[2 * sx][2], sc[2 * sx][3]); pw.z = cvt_pk_bf16(sc[2 * sx + 1][0], sc[2 * sx + 1][1]); pw.w = cvt_pk_bf16(sc[2 * sx + 1][2], sc[2 * sx + 1][3]);
;             pf[sx] = __builtin_bit_cast(bf16x8, pw); }
;         const int nitem = (item + 1 < item0 + 2) ? item + 1 : 512;
;         const bf16_t* nkvb = (const bf16_t*)(ws + OFF_MKV) + (size_t)(((nitem < 512 ? nitem : item) >> 7) * 256) * 4096 + (((nitem < 512 ? nitem : item) >> 5) & 3) * 512;
;         for (int c = 0; c < 4; ++c) {
;             LAS unsigned char* buf = lds + (c & 1) * KV_BUF;
;             XSTORE(buf);
;             if (c < 3) XLOAD(kvb, 5 + c); else XLOAD(nkvb, 0);
;             LDS_BARRIER();
;             f32x4 ot[8];
; #pragma unroll
;             for (int c8 = 0; c8 < 8; ++c8) ot[c8] = (f32x4){0.f, 0.f, 0.f, 0.f};
;             const unsigned bb = lbase + (unsigned)((c & 1) * KV_BUF);
; #pragma unroll
;             for (int sx = 0; sx < 8; ++sx) {
;                 const unsigned aA = bb + (unsigned)((32 * sx + 4 * g + (idx >> 2)) * KV_STRIDE + 8 * (idx & 3));
;                 const unsigned aB = aA + 16u * KV_STRIDE;
;                 bf16x8 vf[4];
;                 tr_frag4(aA, aB, vf);
; #pragma unroll
;                 for (int c8 = 0; c8 < 4; ++c8) ot[c8] = mfma16(vf[c8], pf[sx], ot[c8]);
	v_add_f32_e32 v201, v201, v199
	ds_bpermute_b32 v199, v197, v201
	s_waitcnt lgkmcnt(0)
	v_add_f32_e32 v201, v201, v199
	v_div_scale_f32 v199, s[6:7], v201, v201, 1.0
	v_rcp_f32_e32 v200, v199
	s_nop 0
	v_fma_f32 v245, -v199, v200, 1.0
	v_fmac_f32_e32 v200, v245, v200
	v_div_scale_f32 v245, vcc, 1.0, v201, 1.0
	v_mul_f32_e32 v202, v245, v200
	v_fma_f32 v203, -v199, v202, v245
	v_fmac_f32_e32 v202, v203, v200
	v_fma_f32 v199, -v199, v202, v245
	s_nop 1
	v_div_fmas_f32 v199, v199, v200, v202
	v_div_fixup_f32 v245, v199, v201, 1.0
	v_cvt_pk_bf16_f32 v68, v68, v69
	v_cvt_pk_bf16_f32 v69, v70, v71
	v_cvt_pk_bf16_f32 v70, v72, v73
	v_cvt_pk_bf16_f32 v71, v74, v75
	v_cvt_pk_bf16_f32 v76, v76, v77
	v_cvt_pk_bf16_f32 v77, v78, v79
	v_cvt_pk_bf16_f32 v78, v80, v81
	v_cvt_pk_bf16_f32 v79, v82, v83
	v_cvt_pk_bf16_f32 v84, v84, v85
	v_cvt_pk_bf16_f32 v85, v86, v87
	v_cvt_pk_bf16_f32 v86, v88, v89
	v_cvt_pk_bf16_f32 v87, v90, v91
	v_cvt_pk_bf16_f32 v92, v92, v93
	v_cvt_pk_bf16_f32 v93, v94, v95
	v_cvt_pk_bf16_f32 v94, v96, v97
	v_cvt_pk_bf16_f32 v95, v98, v99
	v_cvt_pk_bf16_f32 v100, v100, v101
	v_cvt_pk_bf16_f32 v101, v102, v103
	v_cvt_pk_bf16_f32 v102, v104, v105
	v_cvt_pk_bf16_f32 v103, v106, v107
	v_cvt_pk_bf16_f32 v108, v108, v109
	v_cvt_pk_bf16_f32 v109, v110, v111
	v_cvt_pk_bf16_f32 v110, v112, v113
	v_cvt_pk_bf16_f32 v111, v114, v115
	v_cvt_pk_bf16_f32 v116, v116, v117
	v_cvt_pk_bf16_f32 v117, v118, v119
	v_cvt_pk_bf16_f32 v118, v120, v121
	v_cvt_pk_bf16_f32 v119, v122, v123
	v_cvt_pk_bf16_f32 v124, v124, v125
	v_cvt_pk_bf16_f32 v125, v126, v127
	v_cvt_pk_bf16_f32 v126, v128, v129
	v_cvt_pk_bf16_f32 v127, v130, v131
	v_and_b32_e32 v204, 63, v212
	v_and_b32_e32 v205, 15, v204
	v_lshrrev_b32_e32 v204, 4, v204
	v_lshrrev_b32_e32 v206, 2, v205
	v_lshl_add_u32 v206, v204, 2, v206
	v_and_b32_e32 v207, 7, v206
	v_lshlrev_b32_e32 v207, 1, v207
	v_bfe_u32 v204, v205, 1, 1
	v_add_u32_e32 v207, v207, v204
	v_and_b32_e32 v204, 1, v205
	v_lshlrev_b32_e32 v204, 3, v204
	v_lshl_add_u32 v206, v206, 8, v204
	v_add_u32_e32 v204, 0, v207
	v_and_b32_e32 v204, 15, v204
	v_lshl_add_u32 v196, v204, 4, v206
	v_add_u32_e32 v204, 2, v207
	v_and_b32_e32 v204, 15, v204
	v_lshl_add_u32 v197, v204, 4, v206
	v_add_u32_e32 v204, 4, v207
	v_and_b32_e32 v204, 15, v204
	v_lshl_add_u32 v198, v204, 4, v206
	v_add_u32_e32 v204, 6, v207
	v_and_b32_e32 v204, 15, v204
	v_lshl_add_u32 v199, v204, 4, v206
	v_add_u32_e32 v204, 8, v207
	v_and_b32_e32 v204, 15, v204
	v_lshl_add_u32 v200, v204, 4, v206
	v_add_u32_e32 v204, 10, v207
	v_and_b32_e32 v204, 15, v204
	v_lshl_add_u32 v201, v204, 4, v206
	v_add_u32_e32 v204, 12, v207
	v_and_b32_e32 v204, 15, v204
	v_lshl_add_u32 v202, v204, 4, v206
	v_add_u32_e32 v204, 14, v207
	v_and_b32_e32 v204, 15, v204
	v_lshl_add_u32 v203, v204, 4, v206
	s_waitcnt vmcnt(0)
	s_mov_b32 s4, 0
.Lxa_pv:
	s_waitcnt vmcnt(16)
	s_barrier
	s_and_b32 s2, s9, 3
	s_lshl_b32 s2, s2, 8
	s_lshr_b32 s3, s9, 2
	s_lshl_b32 s3, s3, 12
	s_add_i32 s2, s2, s3
	s_add_u32 s0, s92, s2
	s_addc_u32 s1, s93, 0
	s_add_i32 s9, s9, 1
	s_mov_b32 m0, s10
	s_nop 0
	global_load_lds_dwordx4 v164, s[0:1]
	s_add_u32 s0, s0, 0x8000
	s_addc_u32 s1, s1, 0
	s_add_i32 m0, s10, 0x400
	s_nop 0
	global_load_lds_dwordx4 v165, s[0:1]
	s_add_u32 s0, s0, 0x8000
	s_addc_u32 s1, s1, 0
	s_add_i32 m0, s10, 0x800
	s_nop 0
	global_load_lds_dwordx4 v164, s[0:1]
	s_add_u32 s0, s0, 0x8000
	s_addc_u32 s1, s1, 0
	s_add_i32 m0, s10, 0xc00
	s_nop 0
	global_load_lds_dwordx4 v165, s[0:1]
	s_add_u32 s0, s0, 0x8000
	s_addc_u32 s1, s1, 0
	s_add_i32 m0, s10, 0x1000
	s_nop 0
	global_load_lds_dwordx4 v164, s[0:1]
	s_add_u32 s0, s0, 0x8000
	s_addc_u32 s1, s1, 0
	s_add_i32 m0, s10, 0x1400
	s_nop 0
	global_load_lds_dwordx4 v165, s[0:1]
	s_add_u32 s0, s0, 0x8000
	s_addc_u32 s1, s1, 0
	s_add_i32 m0, s10, 0x1800
	s_nop 0
	global_load_lds_dwordx4 v164, s[0:1]
	s_add_u32 s0, s0, 0x8000
	s_addc_u32 s1, s1, 0
	s_add_i32 m0, s10, 0x1c00
	s_nop 0
	global_load_lds_dwordx4 v165, s[0:1]
	s_xor_b32 s10, s10, 0x10000
	ds_read_b64_tr_b16 v[72:73], v196
	ds_read_b64_tr_b16 v[80:81], v197
	ds_read_b64_tr_b16 v[74:75], v196 offset:4096
	ds_read_b64_tr_b16 v[82:83], v197 offset:4096
	ds_read_b64_tr_b16 v[88:89], v198
	ds_read_b64_tr_b16 v[96:97], v199
	ds_read_b64_tr_b16 v[90:91], v198 offset:4096
	ds_read_b64_tr_b16 v[98:99], v199 offset:4096
	ds_read_b64_tr_b16 v[104:105], v200
	ds_read_b64_tr_b16 v[112:113], v201
	ds_read_b64_tr_b16 v[106:107], v200 offset:4096
	ds_read_b64_tr_b16 v[114:115], v201 offset:4096
	s_waitcnt lgkmcnt(8)
	ds_read_b64_tr_b16 v[120:121], v202
	ds_read_b64_tr_b16 v[128:129], v203
	ds_read_b64_tr_b16 v[122:123], v202 offset:4096
	ds_read_b64_tr_b16 v[130:131], v203 offset:4096
	v_mfma_f32_16x16x32_bf16 v[132:135], v[72:75], v[4:7], 0
	v_mfma_f32_16x16x32_bf16 v[8:11], v[72:75], v[68:71], 0
	v_mfma_f32_16x16x32_bf16 v[136:139], v[80:83], v[4:7], 0
	v_mfma_f32_16x16x32_bf16 v[16:19], v[80:83], v[68:71], 0
	s_waitcnt lgkmcnt(8)
	ds_read_b64_tr_b16 v[72:73], v196 offset:8192
	ds_read_b64_tr_b16 v[80:81], v197 offset:8192
	ds_read_b64_tr_b16 v[74:75], v196 offset:12288
	ds_read_b64_tr_b16 v[82:83], v197 offset:12288
	v_mfma_f32_16x16x32_bf16 v[140:143], v[88:91], v[4:7], 0
	v_mfma_f32_16x16x32_bf16 v[24:27], v[88:91], v[68:71], 0
	v_mfma_f32_16x16x32_bf16 v[144:147], v[96:99], v[4:7], 0
	v_mfma_f32_16x16x32_bf16 v[32:35], v[96:99], v[68:71], 0
	s_waitcnt lgkmcnt(8)
	ds_read_b64_tr_b16 v[88:89], v198 offset:8192
	ds_read_b64_tr_b16 v[96:97], v199 offset:8192
	ds_read_b64_tr_b16 v[90:91], v198 offset:12288
	ds_read_b64_tr_b16 v[98:99], v199 offset:12288
	v_mfma_f32_16x16x32_bf16 v[148:151], v[104:107], v[4:7], 0
	v_mfma_f32_16x16x32_bf16 v[40:43], v[104:107], v[68:71], 0
	v_mfma_f32_16x16x32_bf16 v[152:155], v[112:115], v[4:7], 0
	v_mfma_f32_16x16x32_bf16 v[48:51], v[112:115], v[68:71], 0
	s_waitcnt lgkmcnt(8)
; __device__ __forceinline__ f32x4 mfma16(bf16x8 a, bf16x8 b, f32x4 c) { return __builtin_amdgcn_mfma_f32_16x16x32_bf16(a, b, c, 0, 0, 0); }
; __device__ void cross_items(const Params& p, LAS unsigned char* lds) {
;     ...
; #pragma unroll
;             for (int sx = 0; sx < 8; ++sx) {
;                 const unsigned aA = bb + (unsigned)((32 * sx + 4 * g + (idx >> 2)) * KV_STRIDE + 8 * (idx & 3));
;                 const unsigned aB = aA + 16u * KV_STRIDE;
;                 bf16x8 vf[4];
;                 tr_frag4(aA, aB, vf);
; #pragma unroll
;                 for (int c8 = 0; c8 < 4; ++c8) ot[c8] = mfma16(vf[c8], pf[sx], ot[c8]);
;                 tr_frag4(aA + 128, aB + 128, vf);
; #pragma unroll
;                 for (int c8 = 0; c8 < 4; ++c8) ot[4 + c8] = mfma16(vf[c8], pf[sx], ot[4 + c8]);
	ds_read_b64_tr_b16 v[104:105], v200 offset:8192
	ds_read_b64_tr_b16 v[112:113], v201 offset:8192
	ds_read_b64_tr_b16 v[106:107], v200 offset:12288
	ds_read_b64_tr_b16 v[114:115], v201 offset:12288
	v_mfma_f32_16x16x32_bf16 v[156:159], v[120:123], v[4:7], 0
	v_mfma_f32_16x16x32_bf16 v[56:59], v[120:123], v[68:71], 0
	v_mfma_f32_16x16x32_bf16 v[160:163], v[128:131], v[4:7], 0
	v_mfma_f32_16x16x32_bf16 v[64:67], v[128:131], v[68:71], 0
	s_waitcnt lgkmcnt(8)
	ds_read_b64_tr_b16 v[120:121], v202 offset:8192
	ds_read_b64_tr_b16 v[128:129], v203 offset:8192
	ds_read_b64_tr_b16 v[122:123], v202 offset:12288
	ds_read_b64_tr_b16 v[130:131], v203 offset:12288
	v_mfma_f32_16x16x32_bf16 v[132:135], v[72:75], v[12:15], v[132:135]
	v_mfma_f32_16x16x32_bf16 v[8:11], v[72:75], v[76:79], v[8:11]
	v_mfma_f32_16x16x32_bf16 v[136:139], v[80:83], v[12:15], v[136:139]
	v_mfma_f32_16x16x32_bf16 v[16:19], v[80:83], v[76:79], v[16:19]
	s_waitcnt lgkmcnt(8)
	ds_read_b64_tr_b16 v[72:73], v196 offset:16384
	ds_read_b64_tr_b16 v[80:81], v197 offset:16384
	ds_read_b64_tr_b16 v[74:75], v196 offset:20480
	ds_read_b64_tr_b16 v[82:83], v197 offset:20480
	v_mfma_f32_16x16x32_bf16 v[140:143], v[88:91], v[12:15], v[140:143]
	v_mfma_f32_16x16x32_bf16 v[24:27], v[88:91], v[76:79], v[24:27]
	v_mfma_f32_16x16x32_bf16 v[144:147], v[96:99], v[12:15], v[144:147]
	v_mfma_f32_16x16x32_bf16 v[32:35], v[96:99], v[76:79], v[32:35]
	s_waitcnt lgkmcnt(8)
	ds_read_b64_tr_b16 v[88:89], v198 offset:16384
	ds_read_b64_tr_b16 v[96:97], v199 offset:16384
	ds_read_b64_tr_b16 v[90:91], v198 offset:20480
	ds_read_b64_tr_b16 v[98:99], v199 offset:20480
	v_mfma_f32_16x16x32_bf16 v[148:151], v[104:107], v[12:15], v[148:151]
	v_mfma_f32_16x16x32_bf16 v[40:43], v[104:107], v[76:79], v[40:43]
	v_mfma_f32_16x16x32_bf16 v[152:155], v[112:115], v[12:15], v[152:155]
	v_mfma_f32_16x16x32_bf16 v[48:51], v[112:115], v[76:79], v[48:51]
	s_waitcnt lgkmcnt(8)
	ds_read_b64_tr_b16 v[104:105], v200 offset:16384
	ds_read_b64_tr_b16 v[112:113], v201 offset:16384
	ds_read_b64_tr_b16 v[106:107], v200 offset:20480
	ds_read_b64_tr_b16 v[114:115], v201 offset:20480
	v_mfma_f32_16x16x32_bf16 v[156:159], v[120:123], v[12:15], v[156:159]
	v_mfma_f32_16x16x32_bf16 v[56:59], v[120:123], v[76:79], v[56:59]
	v_mfma_f32_16x16x32_bf16 v[160:163], v[128:131], v[12:15], v[160:163]
	v_mfma_f32_16x16x32_bf16 v[64:67], v[128:131], v[76:79], v[64:67]
	s_waitcnt lgkmcnt(8)
	ds_read_b64_tr_b16 v[120:121], v202 offset:16384
	ds_read_b64_tr_b16 v[128:129], v203 offset:16384
	ds_read_b64_tr_b16 v[122:123], v202 offset:20480
	ds_read_b64_tr_b16 v[130:131], v203 offset:20480
	v_mfma_f32_16x16x32_bf16 v[132:135], v[72:75], v[20:23], v[132:135]
	v_mfma_f32_16x16x32_bf16 v[8:11], v[72:75], v[84:87], v[8:11]
	v_mfma_f32_16x16x32_bf16 v[136:139], v[80:83], v[20:23], v[136:139]
	v_mfma_f32_16x16x32_bf16 v[16:19], v[80:83], v[84:87], v[16:19]
	s_waitcnt lgkmcnt(8)
	ds_read_b64_tr_b16 v[72:73], v196 offset:24576
	ds_read_b64_tr_b16 v[80:81], v197 offset:24576
	ds_read_b64_tr_b16 v[74:75], v196 offset:28672
	ds_read_b64_tr_b16 v[82:83], v197 offset:28672
	v_mfma_f32_16x16x32_bf16 v[140:143], v[88:91], v[20:23], v[140:143]
	v_mfma_f32_16x16x32_bf16 v[24:27], v[88:91], v[84:87], v[24:27]
	v_mfma_f32_16x16x32_bf16 v[144:147], v[96:99], v[20:23], v[144:147]
	v_mfma_f32_16x16x32_bf16 v[32:35], v[96:99], v[84:87], v[32:35]
	s_waitcnt lgkmcnt(8)
	ds_read_b64_tr_b16 v[88:89], v198 offset:24576
	ds_read_b64_tr_b16 v[96:97], v199 offset:24576
	ds_read_b64_tr_b16 v[90:91], v198 offset:28672
	ds_read_b64_tr_b16 v[98:99], v199 offset:28672
	v_mfma_f32_16x16x32_bf16 v[148:151], v[104:107], v[20:23], v[148:151]
	v_mfma_f32_16x16x32_bf16 v[40:43], v[104:107], v[84:87], v[40:43]
	v_mfma_f32_16x16x32_bf16 v[152:155], v[112:115], v[20:23], v[152:155]
	v_mfma_f32_16x16x32_bf16 v[48:51], v[112:115], v[84:87], v[48:51]
	s_waitcnt lgkmcnt(8)
	ds_read_b64_tr_b16 v[104:105], v200 offset:24576
	ds_read_b64_tr_b16 v[112:113], v201 offset:24576
	ds_read_b64_tr_b16 v[106:107], v200 offset:28672
	ds_read_b64_tr_b16 v[114:115], v201 offset:28672
	v_mfma_f32_16x16x32_bf16 v[156:159], v[120:123], v[20:23], v[156:159]
	v_mfma_f32_16x16x32_bf16 v[56:59], v[120:123], v[84:87], v[56:59]
	v_mfma_f32_16x16x32_bf16 v[160:163], v[128:131], v[20:23], v[160:163]
	v_mfma_f32_16x16x32_bf16 v[64:67], v[128:131], v[84:87], v[64:67]
	s_waitcnt lgkmcnt(8)
	ds_read_b64_tr_b16 v[120:121], v202 offset:24576
	ds_read_b64_tr_b16 v[128:129], v203 offset:24576
	ds_read_b64_tr_b16 v[122:123], v202 offset:28672
	ds_read_b64_tr_b16 v[130:131], v203 offset:28672
	v_mfma_f32_16x16x32_bf16 v[132:135], v[72:75], v[28:31], v[132:135]
	v_mfma_f32_16x16x32_bf16 v[8:11], v[72:75], v[92:95], v[8:11]
	v_mfma_f32_16x16x32_bf16 v[136:139], v[80:83], v[28:31], v[136:139]
	v_mfma_f32_16x16x32_bf16 v[16:19], v[80:83], v[92:95], v[16:19]
	s_waitcnt lgkmcnt(8)
	ds_read_b64_tr_b16 v[72:73], v196 offset:32768
	ds_read_b64_tr_b16 v[80:81], v197 offset:32768
	ds_read_b64_tr_b16 v[74:75], v196 offset:36864
	ds_read_b64_tr_b16 v[82:83], v197 offset:36864
	v_mfma_f32_16x16x32_bf16 v[140:143], v[88:91], v[28:31], v[140:143]
	v_mfma_f32_16x16x32_bf16 v[24:27], v[88:91], v[92:95], v[24:27]
	v_mfma_f32_16x16x32_bf16 v[144:147], v[96:99], v[28:31], v[144:147]
	v_mfma_f32_16x16x32_bf16 v[32:35], v[96:99], v[92:95], v[32:35]
	s_waitcnt lgkmcnt(8)
	ds_read_b64_tr_b16 v[88:89], v198 offset:32768
	ds_read_b64_tr_b16 v[96:97], v199 offset:32768
	ds_read_b64_tr_b16 v[90:91], v198 offset:36864
	ds_read_b64_tr_b16 v[98:99], v199 offset:36864
	v_mfma_f32_16x16x32_bf16 v[148:151], v[104:107], v[28:31], v[148:151]
	v_mfma_f32_16x16x32_bf16 v[40:43], v[104:107], v[92:95], v[40:43]
	v_mfma_f32_16x16x32_bf16 v[152:155], v[112:115], v[28:31], v[152:155]
	v_mfma_f32_16x16x32_bf16 v[48:51], v[112:115], v[92:95], v[48:51]
	s_waitcnt lgkmcnt(8)
; __device__ __forceinline__ f32x4 mfma16(bf16x8 a, bf16x8 b, f32x4 c) { return __builtin_amdgcn_mfma_f32_16x16x32_bf16(a, b, c, 0, 0, 0); }
; __device__ void cross_items(const Params& p, LAS unsigned char* lds) {
;     ...
; #pragma unroll
;             for (int sx = 0; sx < 8; ++sx) {
;                 const unsigned aA = bb + (unsigned)((32 * sx + 4 * g + (idx >> 2)) * KV_STRIDE + 8 * (idx & 3));
;                 const unsigned aB = aA + 16u * KV_STRIDE;
;                 bf16x8 vf[4];
;                 tr_frag4(aA, aB, vf);
; #pragma unroll
;                 for (int c8 = 0; c8 < 4; ++c8) ot[c8] = mfma16(vf[c8], pf[sx], ot[c8]);
;                 tr_frag4(aA + 128, aB + 128, vf);
; #pragma unroll
;                 for (int c8 = 0; c8 < 4; ++c8) ot[4 + c8] = mfma16(vf[c8], pf[sx], ot[4 + c8]);
	ds_read_b64_tr_b16 v[104:105], v200 offset:32768
	ds_read_b64_tr_b16 v[112:113], v201 offset:32768
	ds_read_b64_tr_b16 v[106:107], v200 offset:36864
	ds_read_b64_tr_b16 v[114:115], v201 offset:36864
	v_mfma_f32_16x16x32_bf16 v[156:159], v[120:123], v[28:31], v[156:159]
	v_mfma_f32_16x16x32_bf16 v[56:59], v[120:123], v[92:95], v[56:59]
	v_mfma_f32_16x16x32_bf16 v[160:163], v[128:131], v[28:31], v[160:163]
	v_mfma_f32_16x16x32_bf16 v[64:67], v[128:131], v[92:95], v[64:67]
	s_waitcnt lgkmcnt(8)
	ds_read_b64_tr_b16 v[120:121], v202 offset:32768
	ds_read_b64_tr_b16 v[128:129], v203 offset:32768
	ds_read_b64_tr_b16 v[122:123], v202 offset:36864
	ds_read_b64_tr_b16 v[130:131], v203 offset:36864
	v_mfma_f32_16x16x32_bf16 v[132:135], v[72:75], v[36:39], v[132:135]
	v_mfma_f32_16x16x32_bf16 v[8:11], v[72:75], v[100:103], v[8:11]
	v_mfma_f32_16x16x32_bf16 v[136:139], v[80:83], v[36:39], v[136:139]
	v_mfma_f32_16x16x32_bf16 v[16:19], v[80:83], v[100:103], v[16:19]
	s_waitcnt lgkmcnt(8)
	ds_read_b64_tr_b16 v[72:73], v196 offset:40960
	ds_read_b64_tr_b16 v[80:81], v197 offset:40960
	ds_read_b64_tr_b16 v[74:75], v196 offset:45056
	ds_read_b64_tr_b16 v[82:83], v197 offset:45056
	v_mfma_f32_16x16x32_bf16 v[140:143], v[88:91], v[36:39], v[140:143]
	v_mfma_f32_16x16x32_bf16 v[24:27], v[88:91], v[100:103], v[24:27]
	v_mfma_f32_16x16x32_bf16 v[144:147], v[96:99], v[36:39], v[144:147]
	v_mfma_f32_16x16x32_bf16 v[32:35], v[96:99], v[100:103], v[32:35]
	s_waitcnt lgkmcnt(8)
	ds_read_b64_tr_b16 v[88:89], v198 offset:40960
	ds_read_b64_tr_b16 v[96:97], v199 offset:40960
	ds_read_b64_tr_b16 v[90:91], v198 offset:45056
	ds_read_b64_tr_b16 v[98:99], v199 offset:45056
	v_mfma_f32_16x16x32_bf16 v[148:151], v[104:107], v[36:39], v[148:151]
	v_mfma_f32_16x16x32_bf16 v[40:43], v[104:107], v[100:103], v[40:43]
	v_mfma_f32_16x16x32_bf16 v[152:155], v[112:115], v[36:39], v[152:155]
	v_mfma_f32_16x16x32_bf16 v[48:51], v[112:115], v[100:103], v[48:51]
	s_waitcnt lgkmcnt(8)
	ds_read_b64_tr_b16 v[104:105], v200 offset:40960
	ds_read_b64_tr_b16 v[112:113], v201 offset:40960
	ds_read_b64_tr_b16 v[106:107], v200 offset:45056
	ds_read_b64_tr_b16 v[114:115], v201 offset:45056
	v_mfma_f32_16x16x32_bf16 v[156:159], v[120:123], v[36:39], v[156:159]
	v_mfma_f32_16x16x32_bf16 v[56:59], v[120:123], v[100:103], v[56:59]
	v_mfma_f32_16x16x32_bf16 v[160:163], v[128:131], v[36:39], v[160:163]
	v_mfma_f32_16x16x32_bf16 v[64:67], v[128:131], v[100:103], v[64:67]
	s_waitcnt lgkmcnt(8)
	ds_read_b64_tr_b16 v[120:121], v202 offset:40960
	ds_read_b64_tr_b16 v[128:129], v203 offset:40960
	ds_read_b64_tr_b16 v[122:123], v202 offset:45056
	ds_read_b64_tr_b16 v[130:131], v203 offset:45056
	v_mfma_f32_16x16x32_bf16 v[132:135], v[72:75], v[44:47], v[132:135]
	v_mfma_f32_16x16x32_bf16 v[8:11], v[72:75], v[108:111], v[8:11]
	v_mfma_f32_16x16x32_bf16 v[136:139], v[80:83], v[44:47], v[136:139]
	v_mfma_f32_16x16x32_bf16 v[16:19], v[80:83], v[108:111], v[16:19]
	s_waitcnt lgkmcnt(8)
	ds_read_b64_tr_b16 v[72:73], v196 offset:49152
	ds_read_b64_tr_b16 v[80:81], v197 offset:49152
	ds_read_b64_tr_b16 v[74:75], v196 offset:53248
	ds_read_b64_tr_b16 v[82:83], v197 offset:53248
	v_mfma_f32_16x16x32_bf16 v[140:143], v[88:91], v[44:47], v[140:143]
	v_mfma_f32_16x16x32_bf16 v[24:27], v[88:91], v[108:111], v[24:27]
	v_mfma_f32_16x16x32_bf16 v[144:147], v[96:99], v[44:47], v[144:147]
	v_mfma_f32_16x16x32_bf16 v[32:35], v[96:99], v[108:111], v[32:35]
	s_waitcnt lgkmcnt(8)
	ds_read_b64_tr_b16 v[88:89], v198 offset:49152
	ds_read_b64_tr_b16 v[96:97], v199 offset:49152
	ds_read_b64_tr_b16 v[90:91], v198 offset:53248
	ds_read_b64_tr_b16 v[98:99], v199 offset:53248
	v_mfma_f32_16x16x32_bf16 v[148:151], v[104:107], v[44:47], v[148:151]
	v_mfma_f32_16x16x32_bf16 v[40:43], v[104:107], v[108:111], v[40:43]
	v_mfma_f32_16x16x32_bf16 v[152:155], v[112:115], v[44:47], v[152:155]
	v_mfma_f32_16x16x32_bf16 v[48:51], v[112:115], v[108:111], v[48:51]
	s_waitcnt lgkmcnt(8)
	ds_read_b64_tr_b16 v[104:105], v200 offset:49152
	ds_read_b64_tr_b16 v[112:113], v201 offset:49152
	ds_read_b64_tr_b16 v[106:107], v200 offset:53248
	ds_read_b64_tr_b16 v[114:115], v201 offset:53248
	v_mfma_f32_16x16x32_bf16 v[156:159], v[120:123], v[44:47], v[156:159]
	v_mfma_f32_16x16x32_bf16 v[56:59], v[120:123], v[108:111], v[56:59]
	v_mfma_f32_16x16x32_bf16 v[160:163], v[128:131], v[44:47], v[160:163]
	v_mfma_f32_16x16x32_bf16 v[64:67], v[128:131], v[108:111], v[64:67]
	s_waitcnt lgkmcnt(8)
	ds_read_b64_tr_b16 v[120:121], v202 offset:49152
	ds_read_b64_tr_b16 v[128:129], v203 offset:49152
	ds_read_b64_tr_b16 v[122:123], v202 offset:53248
	ds_read_b64_tr_b16 v[130:131], v203 offset:53248
	v_mfma_f32_16x16x32_bf16 v[132:135], v[72:75], v[52:55], v[132:135]
	v_mfma_f32_16x16x32_bf16 v[8:11], v[72:75], v[116:119], v[8:11]
	v_mfma_f32_16x16x32_bf16 v[136:139], v[80:83], v[52:55], v[136:139]
	v_mfma_f32_16x16x32_bf16 v[16:19], v[80:83], v[116:119], v[16:19]
	s_waitcnt lgkmcnt(8)
	ds_read_b64_tr_b16 v[72:73], v196 offset:57344
	ds_read_b64_tr_b16 v[80:81], v197 offset:57344
	ds_read_b64_tr_b16 v[74:75], v196 offset:61440
	ds_read_b64_tr_b16 v[82:83], v197 offset:61440
	v_mfma_f32_16x16x32_bf16 v[140:143], v[88:91], v[52:55], v[140:143]
	v_mfma_f32_16x16x32_bf16 v[24:27], v[88:91], v[116:119], v[24:27]
	v_mfma_f32_16x16x32_bf16 v[144:147], v[96:99], v[52:55], v[144:147]
	v_mfma_f32_16x16x32_bf16 v[32:35], v[96:99], v[116:119], v[32:35]
	s_waitcnt lgkmcnt(8)
; __device__ __forceinline__ unsigned cvt_pk_bf16(float lo, float hi) { const f32x2v v = {lo, hi}; const b16x2v r = __builtin_convertvector(v, b16x2v); return __builtin_bit_cast(unsigned, r); }
; __device__ void cross_items(const Params& p, LAS unsigned char* lds) {
;     ...
; #pragma unroll
;             for (int c8 = 0; c8 < 8; ++c8) { u32x2 wv; wv.x = cvt_pk_bf16(ot[c8][0] * inv, ot[c8][1] * inv); wv.y = cvt_pk_bf16(ot[c8][2] * inv, ot[c8][3] * inv);
;                 *(u32x2*)(oc + tok * DM + head * 512 + c * 128 + 16 * c8 + 4 * g) = wv; }
;         }
	ds_read_b64_tr_b16 v[88:89], v198 offset:57344
	ds_read_b64_tr_b16 v[96:97], v199 offset:57344
	ds_read_b64_tr_b16 v[90:91], v198 offset:61440
	ds_read_b64_tr_b16 v[98:99], v199 offset:61440
	v_mfma_f32_16x16x32_bf16 v[148:151], v[104:107], v[52:55], v[148:151]
	v_mfma_f32_16x16x32_bf16 v[40:43], v[104:107], v[116:119], v[40:43]
	v_mfma_f32_16x16x32_bf16 v[152:155], v[112:115], v[52:55], v[152:155]
	v_mfma_f32_16x16x32_bf16 v[48:51], v[112:115], v[116:119], v[48:51]
	s_waitcnt lgkmcnt(8)
	ds_read_b64_tr_b16 v[104:105], v200 offset:57344
	ds_read_b64_tr_b16 v[112:113], v201 offset:57344
	ds_read_b64_tr_b16 v[106:107], v200 offset:61440
	ds_read_b64_tr_b16 v[114:115], v201 offset:61440
	v_mfma_f32_16x16x32_bf16 v[156:159], v[120:123], v[52:55], v[156:159]
	v_mfma_f32_16x16x32_bf16 v[56:59], v[120:123], v[116:119], v[56:59]
	v_mfma_f32_16x16x32_bf16 v[160:163], v[128:131], v[52:55], v[160:163]
	v_mfma_f32_16x16x32_bf16 v[64:67], v[128:131], v[116:119], v[64:67]
	s_waitcnt lgkmcnt(8)
	ds_read_b64_tr_b16 v[120:121], v202 offset:57344
	ds_read_b64_tr_b16 v[128:129], v203 offset:57344
	ds_read_b64_tr_b16 v[122:123], v202 offset:61440
	ds_read_b64_tr_b16 v[130:131], v203 offset:61440
	v_mfma_f32_16x16x32_bf16 v[132:135], v[72:75], v[60:63], v[132:135]
	v_mfma_f32_16x16x32_bf16 v[8:11], v[72:75], v[124:127], v[8:11]
	v_mfma_f32_16x16x32_bf16 v[136:139], v[80:83], v[60:63], v[136:139]
	v_mfma_f32_16x16x32_bf16 v[16:19], v[80:83], v[124:127], v[16:19]
	s_waitcnt lgkmcnt(8)
	v_mfma_f32_16x16x32_bf16 v[140:143], v[88:91], v[60:63], v[140:143]
	v_mfma_f32_16x16x32_bf16 v[24:27], v[88:91], v[124:127], v[24:27]
	v_mfma_f32_16x16x32_bf16 v[144:147], v[96:99], v[60:63], v[144:147]
	v_mfma_f32_16x16x32_bf16 v[32:35], v[96:99], v[124:127], v[32:35]
	s_waitcnt lgkmcnt(4)
	v_mfma_f32_16x16x32_bf16 v[148:151], v[104:107], v[60:63], v[148:151]
	v_mfma_f32_16x16x32_bf16 v[40:43], v[104:107], v[124:127], v[40:43]
	v_mfma_f32_16x16x32_bf16 v[152:155], v[112:115], v[60:63], v[152:155]
	v_mfma_f32_16x16x32_bf16 v[48:51], v[112:115], v[124:127], v[48:51]
	s_waitcnt lgkmcnt(0)
	v_mfma_f32_16x16x32_bf16 v[156:159], v[120:123], v[60:63], v[156:159]
	v_mfma_f32_16x16x32_bf16 v[56:59], v[120:123], v[124:127], v[56:59]
	v_mfma_f32_16x16x32_bf16 v[160:163], v[128:131], v[60:63], v[160:163]
	v_mfma_f32_16x16x32_bf16 v[64:67], v[128:131], v[124:127], v[64:67]
	s_nop 7
	s_nop 7
	v_mul_f32_e32 v230, v244, v132
	v_mul_f32_e32 v231, v244, v133
	v_mul_f32_e32 v232, v244, v134
	v_mul_f32_e32 v233, v244, v135
	v_cvt_pk_bf16_f32 v230, v230, v231
	v_cvt_pk_bf16_f32 v231, v232, v233
	global_store_dwordx2 v248, v[230:231], s[92:93]
	v_mul_f32_e32 v234, v244, v136
	v_mul_f32_e32 v235, v244, v137
	v_mul_f32_e32 v236, v244, v138
	v_mul_f32_e32 v237, v244, v139
	v_cvt_pk_bf16_f32 v234, v234, v235
	v_cvt_pk_bf16_f32 v235, v236, v237
	global_store_dwordx2 v248, v[234:235], s[92:93] offset:32
	v_mul_f32_e32 v230, v244, v140
	v_mul_f32_e32 v231, v244, v141
	v_mul_f32_e32 v232, v244, v142
	v_mul_f32_e32 v233, v244, v143
	v_cvt_pk_bf16_f32 v230, v230, v231
	v_cvt_pk_bf16_f32 v231, v232, v233
	global_store_dwordx2 v248, v[230:231], s[92:93] offset:64
	v_mul_f32_e32 v234, v244, v144
	v_mul_f32_e32 v235, v244, v145
	v_mul_f32_e32 v236, v244, v146
	v_mul_f32_e32 v237, v244, v147
	v_cvt_pk_bf16_f32 v234, v234, v235
	v_cvt_pk_bf16_f32 v235, v236, v237
	global_store_dwordx2 v248, v[234:235], s[92:93] offset:96
	v_mul_f32_e32 v230, v244, v148
	v_mul_f32_e32 v231, v244, v149
	v_mul_f32_e32 v232, v244, v150
	v_mul_f32_e32 v233, v244, v151
	v_cvt_pk_bf16_f32 v230, v230, v231
	v_cvt_pk_bf16_f32 v231, v232, v233
	global_store_dwordx2 v248, v[230:231], s[92:93] offset:128
	v_mul_f32_e32 v234, v244, v152
	v_mul_f32_e32 v235, v244, v153
	v_mul_f32_e32 v236, v244, v154
	v_mul_f32_e32 v237, v244, v155
	v_cvt_pk_bf16_f32 v234, v234, v235
	v_cvt_pk_bf16_f32 v235, v236, v237
	global_store_dwordx2 v248, v[234:235], s[92:93] offset:160
	v_mul_f32_e32 v230, v244, v156
	v_mul_f32_e32 v231, v244, v157
	v_mul_f32_e32 v232, v244, v158
	v_mul_f32_e32 v233, v244, v159
	v_cvt_pk_bf16_f32 v230, v230, v231
	v_cvt_pk_bf16_f32 v231, v232, v233
	global_store_dwordx2 v248, v[230:231], s[92:93] offset:192
	v_mul_f32_e32 v234, v244, v160
	v_mul_f32_e32 v235, v244, v161
	v_mul_f32_e32 v236, v244, v162
	v_mul_f32_e32 v237, v244, v163
	v_cvt_pk_bf16_f32 v234, v234, v235
	v_cvt_pk_bf16_f32 v235, v236, v237
	global_store_dwordx2 v248, v[234:235], s[92:93] offset:224
	v_add_u32_e32 v248, 0x100, v248
	v_mul_f32_e32 v230, v245, v8
	v_mul_f32_e32 v231, v245, v9
	v_mul_f32_e32 v232, v245, v10
	v_mul_f32_e32 v233, v245, v11
	v_cvt_pk_bf16_f32 v230, v230, v231
	v_cvt_pk_bf16_f32 v231, v232, v233
	global_store_dwordx2 v249, v[230:231], s[92:93]
	v_mul_f32_e32 v234, v245, v16
	v_mul_f32_e32 v235, v245, v17
	v_mul_f32_e32 v236, v245, v18
	v_mul_f32_e32 v237, v245, v19
	v_cvt_pk_bf16_f32 v234, v234, v235
	v_cvt_pk_bf16_f32 v235, v236, v237
	global_store_dwordx2 v249, v[234:235], s[92:93] offset:32
	v_mul_f32_e32 v230, v245, v24
	v_mul_f32_e32 v231, v245, v25
	v_mul_f32_e32 v232, v245, v26
	v_mul_f32_e32 v233, v245, v27
	v_cvt_pk_bf16_f32 v230, v230, v231
	v_cvt_pk_bf16_f32 v231, v232, v233
	global_store_dwordx2 v249, v[230:231], s[92:93] offset:64
	v_mul_f32_e32 v234, v245, v32
	v_mul_f32_e32 v235, v245, v33
	v_mul_f32_e32 v236, v245, v34
	v_mul_f32_e32 v237, v245, v35
	v_cvt_pk_bf16_f32 v234, v234, v235
	v_cvt_pk_bf16_f32 v235, v236, v237
	global_store_dwordx2 v249, v[234:235], s[92:93] offset:96
	v_mul_f32_e32 v230, v245, v40
	v_mul_f32_e32 v231, v245, v41
	v_mul_f32_e32 v232, v245, v42
	v_mul_f32_e32 v233, v245, v43
	v_cvt_pk_bf16_f32 v230, v230, v231
	v_cvt_pk_bf16_f32 v231, v232, v233
	global_store_dwordx2 v249, v[230:231], s[92:93] offset:128
	v_mul_f32_e32 v234, v245, v48
	v_mul_f32_e32 v235, v245, v49
	v_mul_f32_e32 v236, v245, v50
	v_mul_f32_e32 v237, v245, v51
	v_cvt_pk_bf16_f32 v234, v234, v235
	v_cvt_pk_bf16_f32 v235, v236, v237
	global_store_dwordx2 v249, v[234:235], s[92:93] offset:160
	v_mul_f32_e32 v230, v245, v56
	v_mul_f32_e32 v231, v245, v57
	v_mul_f32_e32 v232, v245, v58
	v_mul_f32_e32 v233, v245, v59
	v_cvt_pk_bf16_f32 v230, v230, v231
	v_cvt_pk_bf16_f32 v231, v232, v233
	global_store_dwordx2 v249, v[230:231], s[92:93] offset:192
	v_mul_f32_e32 v234, v245, v64
	v_mul_f32_e32 v235, v245, v65
	v_mul_f32_e32 v236, v245, v66
	v_mul_f32_e32 v237, v245, v67
	v_cvt_pk_bf16_f32 v234, v234, v235
	v_cvt_pk_bf16_f32 v235, v236, v237
	global_store_dwordx2 v249, v[234:235], s[92:93] offset:224
	v_add_u32_e32 v249, 0x100, v249
	v_xor_b32_e32 v196, 0x10000, v196
	v_xor_b32_e32 v197, 0x10000, v197
	v_xor_b32_e32 v198, 0x10000, v198
	v_xor_b32_e32 v199, 0x10000, v199
	v_xor_b32_e32 v200, 0x10000, v200
	v_xor_b32_e32 v201, 0x10000, v201
	v_xor_b32_e32 v202, 0x10000, v202
	v_xor_b32_e32 v203, 0x10000, v203
	s_add_i32 s4, s4, 1
	s_cmp_lt_u32 s4, 4
	s_cbranch_scc1 .Lxa_pv
	s_waitcnt vmcnt(0)
	s_waitcnt lgkmcnt(0)
	s_barrier
